# v55 + s5_pass<2>: Toeplitz fragments staged once per group in LDS/VGPRs (no per-tile global reloads) and the four uv loads issued at the top of the tile with xf (removes 10 serial load->wait round tri
# speedup vs baseline: 1.0054x; 1.0054x over previous
; __device__ __forceinline__ unsigned pk2(float lo, float hi) { unsigned r; asm("v_cvt_pk_bf16_f32 %0, %1, %2" : "=v"(r) : "v"(lo), "v"(hi)); return r; }
; __device__ __forceinline__ float bflo(unsigned w) { return __uint_as_float(w << 16); }
; __device__ __forceinline__ float bfhi(unsigned w) { return __uint_as_float(w & 0xffff0000u); }
; __device__ __forceinline__ float gelu_tanh(float x) { const float u = 0.7978845608028654f * (x + 0.044715f * x * x * x); return x * __builtin_amdgcn_rcpf(1.f + fexp(-2.f * u)); }
; __device__ __forceinline__ void lru_apply(CArgs& a, int l, int panel) {
;     ...
;     for (int tile = 0; tile < 16; ++tile) {
;         const int t = tile * 16 + fr;
;         const u32x4 ab0 = abn[0], ab1 = abn[1], gv = gn; const f32x4 c0 = cn[0], c1 = cn[1], c2 = cn[2], c3 = cn[3];
;         if (tile + 1 < 16) LRU2_LOAD(tile + 1);
;         float o[8];
; #pragma unroll
;         for (int k = 0; k < 4; ++k) {
;             o[k] = bflo(ab0[k]) * hin[k] + bfhi(ab0[k]); o[4 + k] = bflo(ab1[k]) * hin[4 + k] + bfhi(ab1[k]);
;         }
; #pragma unroll
;         for (int k = 0; k < 4; ++k) { o[2 * k] *= gelu_tanh(bflo(gv[k])); o[2 * k + 1] *= gelu_tanh(bfhi(gv[k])); }
;         u32x4 w; w.x = pk2(o[0], o[1]); w.y = pk2(o[2], o[3]); w.z = pk2(o[4], o[5]); w.w = pk2(o[6], o[7]);
;         *(u32x4*)(MIX + (size_t)t * 2048 + (768 + ch0) * 2) = w;
;         hin[0] = c0[0] * hin[0] + c0[1]; hin[1] = c0[2] * hin[1] + c0[3]; hin[2] = c1[0] * hin[2] + c1[1]; hin[3] = c1[2] * hin[3] + c1[3];
;         hin[4] = c2[0] * hin[4] + c2[1]; hin[5] = c2[2] * hin[5] + c2[3]; hin[6] = c3[0] * hin[6] + c3[1]; hin[7] = c3[2] * hin[7] + c3[3];
;     }
.LBB0_361:
	s_waitcnt vmcnt(1)
	v_mov_b64_e32 v[64:65], v[12:13]
	v_mov_b64_e32 v[62:63], v[10:11]
	v_lshlrev_b32_e32 v81, 16, v62
	v_and_b32_e32 v79, 0xffff0000, v42
	v_lshlrev_b32_e32 v80, 16, v42
	v_mul_f32_e32 v42, 0x3d372713, v81
	v_mul_f32_e32 v42, v42, v81
	v_mov_b32_e32 v82, v81
	v_fmac_f32_e32 v82, v42, v82
	v_mul_f32_e32 v42, 0x3f4c422a, v82
	v_mul_f32_e32 v42, -2.0, v42
	v_mul_f32_e32 v42, 0x3fb8aa3b, v42
	v_exp_f32_e32 v42, v42
	v_mov_b32_e32 v82, v6
	v_and_b32_e32 v85, 0xffff0000, v43
	v_and_b32_e32 v87, 0xffff0000, v44
	v_add_f32_e32 v42, 1.0, v42
	v_rcp_f32_e32 v83, v42
	v_and_b32_e32 v88, 0xffff0000, v45
	v_lshl_add_u64 v[10:11], s[2:3], 0, v[74:75]
	s_mov_b64 s[8:9], 0x2e004000
	v_pk_mul_f32 v[80:81], v[82:83], v[80:81]
	s_mov_b32 s1, 0x2e004000
	v_add_f32_e32 v42, v80, v79
	v_mul_f32_e32 v79, v42, v81
	v_lshlrev_b32_e32 v42, 16, v43
	v_and_b32_e32 v43, 0xffff0000, v62
	v_mul_f32_e32 v62, 0x3d372713, v43
	v_mul_f32_e32 v62, v62, v43
	v_mov_b32_e32 v80, v43
	v_fmac_f32_e32 v80, v62, v80
	v_mul_f32_e32 v62, 0x3f4c422a, v80
	v_mul_f32_e32 v62, -2.0, v62
	v_mul_f32_e32 v62, 0x3fb8aa3b, v62
	v_exp_f32_e32 v62, v62
	v_mov_b32_e32 v80, v7
	v_lshl_add_u64 v[12:13], v[10:11], 0, s[8:9]
	v_add_co_u32_e32 v10, vcc, s1, v10
	v_add_f32_e32 v62, 1.0, v62
	v_rcp_f32_e32 v81, v62
	v_addc_co_u32_e32 v11, vcc, 0, v11, vcc
	v_lshl_add_u64 v[46:47], s[2:3], 0, v[70:71]
	v_pk_mul_f32 v[42:43], v[80:81], v[42:43]
	s_mov_b64 s[8:9], 0x32000800
	v_add_f32_e32 v42, v42, v85
	v_mul_f32_e32 v62, v42, v43
	v_lshlrev_b32_e32 v43, 16, v63
	v_lshlrev_b32_e32 v42, 16, v44
	v_mul_f32_e32 v44, 0x3d372713, v43
	v_mul_f32_e32 v44, v44, v43
	v_mov_b32_e32 v80, v43
	v_fmac_f32_e32 v80, v44, v80
	v_mul_f32_e32 v44, 0x3f4c422a, v80
	v_mul_f32_e32 v44, -2.0, v44
	v_mul_f32_e32 v44, 0x3fb8aa3b, v44
	v_exp_f32_e32 v44, v44
	v_mov_b32_e32 v80, v8
	v_lshl_add_u64 v[58:59], v[46:47], 0, s[8:9]
	v_add_co_u32_e32 v46, vcc, s5, v46
	v_add_f32_e32 v44, 1.0, v44
	v_rcp_f32_e32 v81, v44
	global_load_dwordx4 v[18:21], v[10:11], off
	global_load_dwordx4 v[14:17], v[12:13], off offset:16
	v_lshl_add_u64 v[10:11], s[2:3], 0, v[72:73]
	v_addc_co_u32_e32 v47, vcc, 0, v47, vcc
	v_pk_mul_f32 v[42:43], v[80:81], v[42:43]
	global_load_dwordx4 v[10:13], v[10:11], off
	v_add_f32_e32 v42, v42, v87
	v_mul_f32_e32 v80, v42, v43
	v_and_b32_e32 v43, 0xffff0000, v63
	v_mul_f32_e32 v44, 0x3d372713, v43
	v_lshlrev_b32_e32 v42, 16, v45
	v_mul_f32_e32 v44, v44, v43
	v_mov_b32_e32 v45, v43
	v_fmac_f32_e32 v45, v44, v45
	v_mul_f32_e32 v44, 0x3f4c422a, v45
	v_mul_f32_e32 v44, -2.0, v44
	v_mul_f32_e32 v44, 0x3fb8aa3b, v44
	v_exp_f32_e32 v44, v44
	global_load_dwordx4 v[46:49], v[46:47], off offset:2048
	s_nop 0
	global_load_dwordx4 v[50:53], v[58:59], off offset:48
	global_load_dwordx4 v[54:57], v[58:59], off offset:32
	s_nop 0
	global_load_dwordx4 v[58:61], v[58:59], off offset:16
	v_and_b32_e32 v84, 0xffff0000, v38
	v_and_b32_e32 v86, 0xffff0000, v39
	v_add_f32_e32 v44, 1.0, v44
	v_rcp_f32_e32 v45, v44
	v_mov_b32_e32 v44, v9
	v_and_b32_e32 v77, 0xffff0000, v40
	v_and_b32_e32 v78, 0xffff0000, v41
	v_pk_mul_f32 v[42:43], v[44:45], v[42:43]
	s_add_i32 s4, s4, -1
	v_add_f32_e32 v42, v42, v88
	v_mul_f32_e32 v63, v42, v43
	v_lshlrev_b32_e32 v43, 16, v64
	v_lshlrev_b32_e32 v42, 16, v38
	v_mul_f32_e32 v38, 0x3d372713, v43
	v_mul_f32_e32 v38, v38, v43
	v_mov_b32_e32 v44, v43
	v_fmac_f32_e32 v44, v38, v44
	v_mul_f32_e32 v38, 0x3f4c422a, v44
	v_mul_f32_e32 v38, -2.0, v38
	v_mul_f32_e32 v38, 0x3fb8aa3b, v38
	v_exp_f32_e32 v38, v38
	v_mov_b32_e32 v44, v2
	v_lshl_add_u64 v[70:71], v[70:71], 0, s[28:29]
	v_lshl_add_u64 v[72:73], v[72:73], 0, s[12:13]
	v_add_f32_e32 v38, 1.0, v38
	v_rcp_f32_e32 v45, v38
	v_lshl_add_u64 v[74:75], v[74:75], 0, s[30:31]
	s_cmp_lg_u32 s4, 0
	v_pk_mul_f32 v[42:43], v[44:45], v[42:43]
	s_nop 0
	v_add_f32_e32 v38, v42, v84
	v_mul_f32_e32 v44, v38, v43
	v_lshlrev_b32_e32 v38, 16, v39
	v_and_b32_e32 v39, 0xffff0000, v64
	v_mul_f32_e32 v42, 0x3d372713, v39
	v_mul_f32_e32 v42, v42, v39
	v_mov_b32_e32 v43, v39
	v_fmac_f32_e32 v43, v42, v43
	v_mul_f32_e32 v42, 0x3f4c422a, v43
	v_mul_f32_e32 v42, -2.0, v42
	v_mul_f32_e32 v42, 0x3fb8aa3b, v42
	v_exp_f32_e32 v42, v42
	s_nop 0
	v_add_f32_e32 v42, 1.0, v42
	v_rcp_f32_e32 v43, v42
	v_mov_b32_e32 v42, v3
	v_pk_mul_f32 v[38:39], v[42:43], v[38:39]
	s_nop 0
	v_add_f32_e32 v38, v38, v86
	v_mul_f32_e32 v45, v38, v39
	v_lshlrev_b32_e32 v39, 16, v65
	v_lshlrev_b32_e32 v38, 16, v40
	v_mul_f32_e32 v40, 0x3d372713, v39
	v_mul_f32_e32 v40, v40, v39
	v_mov_b32_e32 v42, v39
	v_fmac_f32_e32 v42, v40, v42
	v_mul_f32_e32 v40, 0x3f4c422a, v42
	v_mul_f32_e32 v40, -2.0, v40
	v_mul_f32_e32 v40, 0x3fb8aa3b, v40
	v_exp_f32_e32 v40, v40
	v_mov_b32_e32 v42, v4
	v_add_f32_e32 v40, 1.0, v40
	v_rcp_f32_e32 v43, v40
	s_nop 0
	v_pk_mul_f32 v[38:39], v[42:43], v[38:39]
	s_nop 0
	v_add_f32_e32 v38, v38, v77
	v_mul_f32_e32 v42, v38, v39
	v_and_b32_e32 v39, 0xffff0000, v65
	v_mul_f32_e32 v40, 0x3d372713, v39
	v_lshlrev_b32_e32 v38, 16, v41
	v_mul_f32_e32 v40, v40, v39
	v_mov_b32_e32 v41, v39
	v_fmac_f32_e32 v41, v40, v41
	v_mul_f32_e32 v40, 0x3f4c422a, v41
	v_mul_f32_e32 v40, -2.0, v40
	v_mul_f32_e32 v40, 0x3fb8aa3b, v40
	v_exp_f32_e32 v40, v40
	s_nop 0
	v_add_f32_e32 v40, 1.0, v40
	v_rcp_f32_e32 v77, v40
	v_cvt_pk_bf16_f32 v40, v44, v45
	s_nop 0
	v_pk_mul_f32 v[38:39], v[76:77], v[38:39]
	s_nop 0
	v_add_f32_e32 v38, v38, v78
	v_mul_f32_e32 v41, v38, v39
	v_cvt_pk_bf16_f32 v38, v79, v62
	v_cvt_pk_bf16_f32 v39, v80, v63
	v_cvt_pk_bf16_f32 v41, v42, v41
	v_lshl_add_u64 v[42:43], s[2:3], 0, v[68:69]
	global_store_dwordx4 v[42:43], v[38:41], off
	s_waitcnt vmcnt(7)
	v_mov_b64_e32 v[44:45], v[20:21]
	v_lshl_add_u64 v[68:69], v[68:69], 0, s[14:15]
	v_mov_b32_e32 v38, v34
	v_mov_b32_e32 v39, v36
	v_mov_b32_e32 v36, v35
	v_mov_b32_e32 v34, v30
	v_mov_b32_e32 v35, v32
	v_mov_b32_e32 v32, v31
	v_mov_b32_e32 v30, v26
	v_mov_b32_e32 v31, v28
	v_mov_b32_e32 v28, v27
	v_mov_b32_e32 v26, v22
	v_mov_b32_e32 v27, v24
	v_mov_b32_e32 v24, v23
	v_pk_fma_f32 v[6:7], v[38:39], v[6:7], v[36:37]
	v_pk_fma_f32 v[8:9], v[34:35], v[8:9], v[32:33]
	v_pk_fma_f32 v[2:3], v[30:31], v[2:3], v[28:29]
	v_pk_fma_f32 v[4:5], v[26:27], v[4:5], v[24:25]
	s_waitcnt vmcnt(6)
	v_mov_b64_e32 v[40:41], v[16:17]
	s_waitcnt vmcnt(3)
	v_mov_b64_e32 v[22:23], v[50:51]
	s_waitcnt vmcnt(2)
	v_mov_b64_e32 v[26:27], v[54:55]
	s_waitcnt vmcnt(1)
	v_mov_b64_e32 v[30:31], v[58:59]
	v_mov_b64_e32 v[34:35], v[46:47]
	v_mov_b64_e32 v[38:39], v[14:15]
	v_mov_b64_e32 v[42:43], v[18:19]
	v_mov_b64_e32 v[24:25], v[52:53]
	v_mov_b64_e32 v[28:29], v[56:57]
	v_mov_b64_e32 v[32:33], v[60:61]
	v_mov_b64_e32 v[36:37], v[48:49]
	v_mov_b32_e32 v76, v5
	s_cbranch_scc1 .LBB0_361
; #define LAS __attribute__((address_space(3)))
; __device__ __forceinline__ unsigned pk2(float lo, float hi) { unsigned r; asm("v_cvt_pk_bf16_f32 %0, %1, %2" : "=v"(r) : "v"(lo), "v"(hi)); return r; }
; __device__ __forceinline__ float bflo(unsigned w) { return __uint_as_float(w << 16); }
; __device__ __forceinline__ float bfhi(unsigned w) { return __uint_as_float(w & 0xffff0000u); }
; __device__ __forceinline__ float gelu_tanh(float x) { const float u = 0.7978845608028654f * (x + 0.044715f * x * x * x); return x * __builtin_amdgcn_rcpf(1.f + fexp(-2.f * u)); }
; __device__ __forceinline__ void lru_apply(CArgs& a, int l, int panel) {
;     ...
;         float o[8];
; #pragma unroll
;         for (int k = 0; k < 4; ++k) {
;             o[k] = bflo(ab0[k]) * hin[k] + bfhi(ab0[k]); o[4 + k] = bflo(ab1[k]) * hin[4 + k] + bfhi(ab1[k]);
;         }
; #pragma unroll
;         for (int k = 0; k < 4; ++k) { o[2 * k] *= gelu_tanh(bflo(gv[k])); o[2 * k + 1] *= gelu_tanh(bfhi(gv[k])); }
;         u32x4 w; w.x = pk2(o[0], o[1]); w.y = pk2(o[2], o[3]); w.z = pk2(o[4], o[5]); w.w = pk2(o[6], o[7]);
;         *(u32x4*)(MIX + (size_t)t * 2048 + (768 + ch0) * 2) = w;
;         hin[0] = c0[0] * hin[0] + c0[1]; hin[1] = c0[2] * hin[1] + c0[3]; hin[2] = c1[0] * hin[2] + c1[1]; hin[3] = c1[2] * hin[3] + c1[3];
;         hin[4] = c2[0] * hin[4] + c2[1]; hin[5] = c2[2] * hin[5] + c2[3]; hin[6] = c3[0] * hin[6] + c3[1]; hin[7] = c3[2] * hin[7] + c3[3];
;     }
; template <int PASS>
; __device__ __forceinline__ void s5_pass(CArgs& a, LAS unsigned char* lds, int l, int panel) {
;     int tid_ = threadIdx.x; asm volatile("" : "+v"(tid_));
;     const int lane = tid_ & 63, wave = __builtin_amdgcn_readfirstlane(tid_ >> 6);
;     unsigned char* ws = a.ws;
;     const int fr = lane & 15, fq = lane >> 4;
;     LAS float* hl = (LAS float*)(lds + wave * 12288);
;     LAS bf16_t* xh = (LAS bf16_t*)(lds + wave * 12288 + 8192);
;     const unsigned char* Zp = ws + WS_PANEL + (size_t)panel * PANEL_BYTES + P_Z;
;     unsigned char* YS5 = ws + WS_PANEL + (size_t)panel * PANEL_BYTES + P_YS5;
;     for (int gi = 0; gi < 2; ++gi) {
;         const int g = 2 * wave + gi;
;         const bf16_t* Wg = (const bf16_t*)(ws + WS_S5W) + (size_t)(l * 16 + g) * 128 * 64;
;         const bf16_t* Mg = (const bf16_t*)(ws + WS_S5M) + (size_t)(l * 16 + g) * 64 * 192;
	v_lshlrev_b32_e32 v25, 16, v10
	v_mul_f32_e32 v24, 0x3d372713, v25
	v_mul_f32_e32 v24, v24, v25
	v_mov_b32_e32 v26, v25
	v_fmac_f32_e32 v26, v24, v26
	v_mul_f32_e32 v24, 0x3f4c422a, v26
	v_mul_f32_e32 v24, -2.0, v24
	v_mul_f32_e32 v24, 0x3fb8aa3b, v24
	v_exp_f32_e32 v26, v24
	v_and_b32_e32 v29, 0xffff0000, v10
	v_and_b32_e32 v28, 0xffff0000, v18
	v_lshlrev_b32_e32 v24, 16, v18
	v_add_f32_e32 v18, 1.0, v26
	v_mul_f32_e32 v10, 0x3d372713, v29
	v_rcp_f32_e32 v27, v18
	v_mul_f32_e32 v10, v10, v29
	v_mov_b32_e32 v18, v29
	v_fmac_f32_e32 v18, v10, v18
	v_mul_f32_e32 v10, 0x3f4c422a, v18
	v_mul_f32_e32 v10, -2.0, v10
	v_mul_f32_e32 v10, 0x3fb8aa3b, v10
	v_exp_f32_e32 v10, v10
	v_mov_b32_e32 v26, v6
	v_pk_mul_f32 v[24:25], v[26:27], v[24:25]
	v_and_b32_e32 v31, 0xffff0000, v19
	v_add_f32_e32 v6, v24, v28
	v_add_f32_e32 v10, 1.0, v10
	v_lshlrev_b32_e32 v28, 16, v19
	v_lshlrev_b32_e32 v19, 16, v11
	v_rcp_f32_e32 v27, v10
	v_mul_f32_e32 v10, 0x3d372713, v19
	v_mul_f32_e32 v10, v10, v19
	v_mov_b32_e32 v18, v19
	v_fmac_f32_e32 v18, v10, v18
	v_mul_f32_e32 v10, 0x3f4c422a, v18
	v_mul_f32_e32 v10, -2.0, v10
	v_mul_f32_e32 v10, 0x3fb8aa3b, v10
	v_exp_f32_e32 v10, v10
	v_mov_b32_e32 v26, v7
	v_mul_f32_e32 v24, v6, v25
	v_pk_mul_f32 v[6:7], v[26:27], v[28:29]
	v_and_b32_e32 v11, 0xffff0000, v11
	v_add_f32_e32 v6, v6, v31
	v_mul_f32_e32 v25, v6, v7
	v_add_f32_e32 v6, 1.0, v10
	v_rcp_f32_e32 v7, v6
	v_mul_f32_e32 v6, 0x3d372713, v11
	v_mul_f32_e32 v6, v6, v11
	v_mov_b32_e32 v10, v11
	v_fmac_f32_e32 v10, v6, v10
	v_mul_f32_e32 v6, 0x3f4c422a, v10
	v_mul_f32_e32 v6, -2.0, v6
	v_mul_f32_e32 v6, 0x3fb8aa3b, v6
	v_exp_f32_e32 v10, v6
	v_lshlrev_b32_e32 v18, 16, v20
	v_mov_b32_e32 v6, v8
	v_pk_mul_f32 v[6:7], v[6:7], v[18:19]
	v_add_f32_e32 v8, 1.0, v10
	v_rcp_f32_e32 v19, v8
	v_and_b32_e32 v33, 0xffff0000, v20
	v_mov_b32_e32 v18, v9
	v_lshlrev_b32_e32 v9, 16, v12
	v_add_f32_e32 v6, v6, v33
	v_lshlrev_b32_e32 v10, 16, v21
	v_mul_f32_e32 v8, 0x3d372713, v9
	v_mul_f32_e32 v20, v6, v7
	v_pk_mul_f32 v[6:7], v[18:19], v[10:11]
	v_mul_f32_e32 v8, v8, v9
	v_mov_b32_e32 v10, v9
	v_fmac_f32_e32 v10, v8, v10
	v_mul_f32_e32 v8, 0x3f4c422a, v10
	v_mul_f32_e32 v8, -2.0, v8
	v_mul_f32_e32 v8, 0x3fb8aa3b, v8
	v_exp_f32_e32 v10, v8
	v_and_b32_e32 v35, 0xffff0000, v21
	v_add_f32_e32 v6, v6, v35
	v_mul_f32_e32 v18, v6, v7
	v_add_f32_e32 v6, 1.0, v10
	v_and_b32_e32 v11, 0xffff0000, v12
	v_rcp_f32_e32 v7, v6
	v_mul_f32_e32 v6, 0x3d372713, v11
	v_mul_f32_e32 v6, v6, v11
	v_mov_b32_e32 v10, v11
	v_fmac_f32_e32 v10, v6, v10
	v_mul_f32_e32 v6, 0x3f4c422a, v10
	v_mul_f32_e32 v6, -2.0, v6
	v_mul_f32_e32 v6, 0x3fb8aa3b, v6
	v_exp_f32_e32 v10, v6
	v_lshlrev_b32_e32 v8, 16, v14
	v_mov_b32_e32 v6, v2
	v_and_b32_e32 v30, 0xffff0000, v14
	v_pk_mul_f32 v[6:7], v[6:7], v[8:9]
	v_mov_b32_e32 v8, v3
	v_add_f32_e32 v2, v6, v30
	v_add_f32_e32 v6, 1.0, v10
	v_rcp_f32_e32 v9, v6
	v_mul_f32_e32 v12, v2, v7
	v_lshlrev_b32_e32 v7, 16, v13
	v_lshlrev_b32_e32 v10, 16, v15
	v_mul_f32_e32 v6, 0x3d372713, v7
	v_pk_mul_f32 v[2:3], v[8:9], v[10:11]
	v_mul_f32_e32 v6, v6, v7
	v_mov_b32_e32 v8, v7
	v_fmac_f32_e32 v8, v6, v8
	v_mul_f32_e32 v6, 0x3f4c422a, v8
	v_mul_f32_e32 v6, -2.0, v6
	v_mul_f32_e32 v6, 0x3fb8aa3b, v6
	v_exp_f32_e32 v8, v6
	v_and_b32_e32 v32, 0xffff0000, v15
	v_add_f32_e32 v2, v2, v32
	v_mul_f32_e32 v10, v2, v3
	v_add_f32_e32 v2, 1.0, v8
	v_and_b32_e32 v9, 0xffff0000, v13
	v_rcp_f32_e32 v3, v2
	v_mul_f32_e32 v2, 0x3d372713, v9
	v_mul_f32_e32 v2, v2, v9
	v_mov_b32_e32 v8, v9
	v_fmac_f32_e32 v8, v2, v8
	v_mul_f32_e32 v2, 0x3f4c422a, v8
	v_mul_f32_e32 v2, -2.0, v2
	v_mul_f32_e32 v2, 0x3fb8aa3b, v2
	v_exp_f32_e32 v8, v2
	v_lshlrev_b32_e32 v6, 16, v16
	v_mov_b32_e32 v2, v4
	v_pk_mul_f32 v[2:3], v[2:3], v[6:7]
	v_add_f32_e32 v4, 1.0, v8
	v_rcp_f32_e32 v7, v4
	v_and_b32_e32 v34, 0xffff0000, v16
	v_lshl_add_u64 v[22:23], s[10:11], 0, v[66:67]
	v_add_f32_e32 v2, v2, v34
	v_lshlrev_b32_e32 v8, 16, v17
	v_mov_b32_e32 v6, v5
	v_and_b32_e32 v36, 0xffff0000, v17
	v_mul_f32_e32 v11, v2, v3
	v_pk_mul_f32 v[2:3], v[6:7], v[8:9]
	v_lshl_add_u64 v[6:7], v[22:23], 0, v[0:1]
	s_mov_b32 s1, 0x1b8000
	v_add_f32_e32 v2, v2, v36
	v_add_co_u32_e32 v6, vcc, s1, v6
	v_readlane_b32 s2, v249, 0
	v_mul_f32_e32 v5, v2, v3
	v_addc_co_u32_e32 v7, vcc, 0, v7, vcc
	v_readlane_b32 s3, v249, 1
	v_cvt_pk_bf16_f32 v2, v24, v25
	v_cvt_pk_bf16_f32 v3, v20, v18
	v_cvt_pk_bf16_f32 v4, v12, v10
	v_cvt_pk_bf16_f32 v5, v11, v5
	global_store_dwordx4 v[6:7], v[2:5], off
	s_load_dwordx2 s[8:9], s[2:3], 0x58
	s_nop 0
	s_load_dwordx2 s[2:3], s[2:3], 0xf8
	v_mov_b32_e32 v140, v189
	v_mov_b32_e32 v137, v1
	v_readfirstlane_b32 s1, v140
	s_ashr_i32 s11, s1, 6
	s_mul_i32 s4, s11, 0x3000
	s_add_i32 s20, s4, 0
	s_lshl_b32 s10, s11, 1
	v_and_b32_e32 v136, 48, v140
	s_waitcnt lgkmcnt(0)
; template <int PASS>
; __device__ __forceinline__ void s5_pass(CArgs& a, LAS unsigned char* lds, int l, int panel) {
;     ...
;     for (int gi = 0; gi < 2; ++gi) {
;         const int g = 2 * wave + gi;
;         const bf16_t* Wg = (const bf16_t*)(ws + WS_S5W) + (size_t)(l * 16 + g) * 128 * 64;
;         const bf16_t* Mg = (const bf16_t*)(ws + WS_S5M) + (size_t)(l * 16 + g) * 64 * 192;
;         bf16x8 wf[8][2];
; #pragma unroll
;         for (int mt = 0; mt < 8; ++mt)
; #pragma unroll
;             for (int ks = 0; ks < 2; ++ks) wf[mt][ks] = *(const bf16x8*)(Wg + (size_t)(16 * mt + fr) * 64 + 32 * ks + 8 * fq);
;         bf16x8 mf[4][4];
;         f32x4 dsk = (f32x4){0.f, 0.f, 0.f, 0.f};
;         if (PASS == 2) {
; #pragma unroll
;             for (int mt = 0; mt < 4; ++mt)
; #pragma unroll
;                 for (int ks = 0; ks < 4; ++ks) mf[mt][ks] = *(const bf16x8*)(Mg + (size_t)(16 * mt + fr) * 192 + 64 + 32 * ks + 8 * fq);
;             dsk = *(const f32x4*)(a.in[11] + l * 256 + g * 16 + 4 * fq);
;         }
;         const float* Ap = (const float*)(ws + WS_S5A) + ((size_t)(l * 16 + g) * 64 + lane) * 4;
;         const float a4r = Ap[0], a4i = Ap[1];
;         float* Hg = (float*)(ws + WS_S5H) + ((size_t)panel * 16 + g) * 128 + 2 * lane;
;         float Hr = 0.f, Hi = 0.f;
;         if (PASS == 2) { Hr = Hg[0]; Hi = Hg[1]; }
	s_add_u32 s4, s2, 0x3200000
	v_lshl_add_u64 v[2:3], s[2:3], 0, v[136:137]
	s_mov_b64 s[18:19], 0x3800000
	s_mov_b32 s61, s37
	s_addc_u32 s5, s3, 0
	v_lshl_add_u64 v[174:175], v[2:3], 0, s[18:19]
	s_lshl_b64 s[18:19], s[60:61], 2
	v_and_b32_e32 v138, 63, v140
	s_add_u32 s8, s8, s18
	s_addc_u32 s9, s9, s19
	v_lshlrev_b32_e32 v0, 4, v138
	v_lshl_add_u64 v[166:167], s[8:9], 0, v[136:137]
	v_lshl_add_u64 v[2:3], s[2:3], 0, v[0:1]
	s_mov_b64 s[8:9], 0x3100000
	v_lshl_add_u64 v[170:171], v[2:3], 0, s[8:9]
	v_readlane_b32 s8, v248, 3
	v_readlane_b32 s9, v248, 4
	s_add_u32 s8, s2, s8
	s_addc_u32 s9, s3, s9
	v_lshlrev_b32_e32 v0, 3, v138
	s_add_i32 s26, s10, s66
	v_and_b32_e32 v142, 15, v140
	v_lshl_add_u64 v[2:3], s[8:9], 0, v[0:1]
	s_mov_b64 s[8:9], 0x3b00000
	s_ashr_i32 s27, s26, 31
	v_lshlrev_b32_e32 v172, 6, v142
	v_lshl_add_u64 v[168:169], v[2:3], 0, s[8:9]
	s_lshl_b64 s[8:9], s[26:27], 14
	v_lshl_add_u64 v[58:59], v[174:175], 0, s[8:9]
	v_lshlrev_b32_e32 v0, 7, v142
	v_or_b32_e32 v176, 0x800, v172
	v_lshl_add_u64 v[14:15], v[58:59], 0, v[0:1]
	v_lshlrev_b32_e32 v0, 1, v176
	v_or_b32_e32 v178, 0xc00, v172
	v_lshl_add_u64 v[22:23], v[58:59], 0, v[0:1]
	v_lshlrev_b32_e32 v0, 1, v178
	v_or_b32_e32 v180, 0x1000, v172
	v_lshl_add_u64 v[30:31], v[58:59], 0, v[0:1]
	v_lshlrev_b32_e32 v0, 1, v180
	v_or_b32_e32 v182, 0x1400, v172
	v_lshl_add_u64 v[38:39], v[58:59], 0, v[0:1]
	v_lshlrev_b32_e32 v0, 1, v182
	v_or_b32_e32 v184, 0x1800, v172
	s_mul_i32 s18, s26, 0x6000
	v_lshl_add_u64 v[46:47], v[58:59], 0, v[0:1]
	v_lshlrev_b32_e32 v0, 1, v184
	v_or_b32_e32 v186, 0x1c00, v172
	s_mul_hi_i32 s19, s26, 0x6000
	v_lshl_add_u64 v[54:55], v[58:59], 0, v[0:1]
	v_lshlrev_b32_e32 v0, 1, v186
	s_add_u32 s18, s4, s18
	v_mul_u32_u24_e32 v188, 0xc0, v142
	v_lshl_add_u64 v[62:63], v[58:59], 0, v[0:1]
	s_addc_u32 s19, s5, s19
	v_lshlrev_b32_e32 v0, 1, v188
	v_lshl_add_u64 v[66:67], s[18:19], 0, v[0:1]
	s_lshl_b64 s[8:9], s[26:27], 10
	v_lshl_add_u64 v[114:115], v[66:67], 0, v[136:137]
	v_lshl_add_u64 v[66:67], v[170:171], 0, s[8:9]
	s_mov_b64 s[38:39], 0x1800
	s_mov_b64 s[8:9], 0x3000
	s_mov_b64 s[40:41], 0x4800
	v_lshl_add_u64 v[94:95], v[114:115], 0, s[38:39]
	v_lshl_add_u64 v[198:199], v[114:115], 0, s[8:9]
	v_lshl_add_u64 v[126:127], v[114:115], 0, s[40:41]
	s_lshl_b32 s26, s11, 5
	s_ashr_i32 s11, s10, 31
	global_load_dwordx4 v[2:5], v[14:15], off
	global_load_dwordx4 v[6:9], v[14:15], off offset:64
	global_load_dwordx4 v[10:13], v[14:15], off offset:2048
	s_nop 0
	global_load_dwordx4 v[14:17], v[14:15], off offset:2112
	s_nop 0
	global_load_dwordx4 v[18:21], v[22:23], off
	s_nop 0
	global_load_dwordx4 v[22:25], v[22:23], off offset:64
	s_nop 0
	global_load_dwordx4 v[26:29], v[30:31], off
	s_nop 0
	global_load_dwordx4 v[30:33], v[30:31], off offset:64
	s_nop 0
	global_load_dwordx4 v[34:37], v[38:39], off
	s_nop 0
	global_load_dwordx4 v[38:41], v[38:39], off offset:64
	s_nop 0
	global_load_dwordx4 v[42:45], v[46:47], off
	s_nop 0
	global_load_dwordx4 v[46:49], v[46:47], off offset:64
	s_nop 0
	global_load_dwordx4 v[50:53], v[54:55], off
	s_nop 0
	global_load_dwordx4 v[54:57], v[54:55], off offset:64
	s_nop 0
	global_load_dwordx4 v[58:61], v[62:63], off
	s_nop 0
	global_load_dwordx4 v[62:65], v[62:63], off offset:64
	s_nop 0
	global_load_dwordx2 v[196:197], v[66:67], off
	s_nop 0
	global_load_dwordx4 v[66:69], v[114:115], off offset:128
	global_load_dwordx4 v[70:73], v[114:115], off offset:192
	global_load_dwordx4 v[74:77], v[114:115], off offset:256
	global_load_dwordx4 v[78:81], v[114:115], off offset:320
	global_load_dwordx4 v[82:85], v[94:95], off offset:128
	global_load_dwordx4 v[86:89], v[94:95], off offset:192
	global_load_dwordx4 v[90:93], v[94:95], off offset:256
	s_nop 0
	global_load_dwordx4 v[94:97], v[94:95], off offset:320
	s_nop 0
	global_load_dwordx4 v[98:101], v[198:199], off offset:128
	global_load_dwordx4 v[102:105], v[198:199], off offset:192
	global_load_dwordx4 v[106:109], v[198:199], off offset:256
	global_load_dwordx4 v[110:113], v[198:199], off offset:320
	global_load_dwordx4 v[114:117], v[126:127], off offset:128
	global_load_dwordx4 v[118:121], v[126:127], off offset:192
	global_load_dwordx4 v[122:125], v[126:127], off offset:256
	s_nop 0
	global_load_dwordx4 v[126:129], v[126:127], off offset:320
	s_ashr_i32 s27, s26, 31
	s_lshl_b64 s[8:9], s[10:11], 9
	v_lshl_add_u64 v[130:131], s[26:27], 2, v[166:167]
	v_lshl_add_u64 v[134:135], v[168:169], 0, s[8:9]
	global_load_dwordx4 v[130:133], v[130:131], off
	v_bfe_u32 v139, v140, 4, 2
	global_load_dwordx2 v[134:135], v[134:135], off
	v_lshlrev_b32_e32 v173, 2, v138
	v_lshlrev_b32_e32 v138, 9, v142
	v_lshlrev_b32_e32 v190, 3, v139
	v_lshlrev_b32_e32 v181, 2, v139
	v_bfe_u32 v141, v140, 5, 1
	v_add3_u32 v238, s20, v138, v136
	v_lshl_add_u64 v[138:139], s[18:19], 0, v[136:137]
	s_andn2_b32 s1, s1, 63
	v_lshl_add_u64 v[202:203], v[138:139], 0, v[0:1]
	v_and_or_b32 v138, v140, 16, s1
	v_mul_u32_u24_e32 v0, 0x1400, v141
	s_movk_i32 s9, 0x5000
	v_ashrrev_i32_e32 v139, 31, v138
	v_mad_u32_u24 v0, v142, s9, v0
	v_lshl_add_u64 v[138:139], v[138:139], 0, v[0:1]
	v_lshl_add_u64 v[208:209], s[2:3], 0, v[138:139]
	v_or_b32_e32 v138, s1, v190
	v_lshl_add_u64 v[204:205], v[202:203], 0, s[38:39]
	v_ashrrev_i32_e32 v139, 31, v138
	s_add_u32 s38, s2, 0xe1c0400
	v_lshlrev_b32_e32 v194, 11, v142
	v_mov_b32_e32 v195, v1
	v_lshl_add_u32 v143, v142, 8, s20
	v_mad_u64_u32 v[140:141], s[18:19], v142, s9, v[138:139]
	s_addc_u32 s39, s3, 0
	v_lshl_add_u64 v[138:139], v[194:195], 0, v[138:139]
	s_mov_b32 s8, 4
	v_add_u32_e32 v239, s20, v173
	v_lshl_add_u64 v[206:207], v[202:203], 0, s[40:41]
	v_mul_hi_u32_u24_e32 v193, 0x5000, v142
	v_mul_u32_u24_e32 v192, 0x5000, v142
	v_lshl_add_u64 v[210:211], s[2:3], 0, v[140:141]
	v_lshl_add_u64 v[212:213], s[38:39], 0, v[138:139]
	v_add_u32_e32 v240, v143, v136
	s_mov_b32 s20, 0xe000000
	s_waitcnt vmcnt(18)
	v_pk_mov_b32 v[200:201], v[196:197], v[196:197] op_sel:[1,0]
	v_lshlrev_b32_e32 v191, 4, v189
	v_lshrrev_b32_e32 v223, 8, v189
	v_lshl_add_u32 v220, v223, 4, v191
	v_add_u32_e32 v220, 0x21000, v220
	v_add_u32_e32 v191, 0x18000, v191
	global_load_dwordx4 v[250:253], v[198:199], off
	global_load_dwordx4 v[162:165], v[198:199], off offset:64
	s_waitcnt vmcnt(0)
	ds_write_b128 v191, v[250:253]
	ds_write_b128 v191, v[162:165] offset:8192
	s_waitcnt lgkmcnt(0)
	global_load_dwordx4 v[250:253], v[206:207], off
	global_load_dwordx4 v[162:165], v[206:207], off offset:64
	s_waitcnt vmcnt(0)
	ds_write_b128 v191, v[250:253] offset:16384
	ds_write_b128 v191, v[162:165] offset:24576
	s_waitcnt lgkmcnt(0)
	global_load_dwordx4 v[162:165], v[202:203], off
	global_load_dwordx4 v[250:253], v[204:205], off
	s_waitcnt vmcnt(0)
	ds_write_b128 v220, v[162:165]
	s_waitcnt lgkmcnt(0)
; #define LAS __attribute__((address_space(3)))
; __device__ __forceinline__ unsigned pk2(float lo, float hi) { unsigned r; asm("v_cvt_pk_bf16_f32 %0, %1, %2" : "=v"(r) : "v"(lo), "v"(hi)); return r; }
; __device__ __forceinline__ void lds_fence() { asm volatile("s_waitcnt lgkmcnt(0)" ::: "memory"); }
; __device__ __forceinline__ f32x4 mfma16(bf16x8 a, bf16x8 b, f32x4 c) { return __builtin_amdgcn_mfma_f32_16x16x32_bf16(a, b, c, 0, 0, 0); }
; template <int PASS>
; __device__ __forceinline__ void s5_pass(CArgs& a, LAS unsigned char* lds, int l, int panel) {
;     ...
;         for (int nt = 0; nt < 4; ++nt) {
;             bf16x8 xf[2];
; #pragma unroll
;             for (int ks = 0; ks < 2; ++ks) xf[ks] = *(const bf16x8*)(Zp + (size_t)(64 * nt + 4 * fr + 2 * ks + (fq >> 1)) * ZROWB + (C_S5U + g * 16 + (fq & 1) * 8) * 2);
; #pragma unroll
;             for (int mt = 0; mt < 8; ++mt) {
;                 f32x4 acc = mfma16(wf[mt][0], xf[0], (f32x4){0.f, 0.f, 0.f, 0.f});
;                 acc = mfma16(wf[mt][1], xf[1], acc);
;                 *(LAS f32x4*)(hl + fr * 128 + 16 * mt + 4 * fq) = acc;
;             }
;             lds_fence();
;             for (int j = 0; j < 16; ++j) {
;                 if (PASS == 2) *(LAS unsigned*)(xh + j * 128 + 2 * lane) = pk2(Hr, Hi);
;                 const f32x2 lc = *(LAS f32x2*)(hl + j * 128 + 2 * lane);
;                 const float nr = a4r * Hr - a4i * Hi + lc.x, ni = a4r * Hi + a4i * Hr + lc.y;
;                 Hr = nr; Hi = ni;
;             }
.LBB0_363:
	v_lshl_add_u64 v[136:137], v[208:209], 0, s[88:89]
	v_add_co_u32_e32 v138, vcc, 0xe000000, v136
	v_add_u32_e32 v241, v239, v173
	s_nop 0
	v_addc_co_u32_e32 v139, vcc, 0, v137, vcc
	global_load_dwordx4 v[138:141], v[138:139], off
	v_add_co_u32_e32 v136, vcc, 0xe002000, v136
	s_waitcnt vmcnt(1)
	v_mul_f32_e32 v150, v201, v135
	v_addc_co_u32_e32 v137, vcc, 0, v137, vcc
	global_load_dwordx4 v[142:145], v[136:137], off offset:2048
	v_mul_f32_e32 v136, v197, v135
	v_cvt_pk_bf16_f32 v151, v134, v135
	v_pk_fma_f32 v[136:137], v[196:197], v[134:135], v[136:137] op_sel_hi:[1,1,0] neg_lo:[0,0,1] neg_hi:[0,0,1]
	v_pk_fma_f32 v[134:135], v[200:201], v[134:135], v[150:151] op_sel_hi:[1,1,0]
	v_lshl_add_u64 v[214:215], v[210:211], 0, s[88:89]
	v_add_co_u32_e32 v216, vcc, s20, v214
	s_add_i32 s8, s8, -1
	s_nop 0
	v_addc_co_u32_e32 v217, vcc, 0, v215, vcc
	v_add_co_u32_e32 v244, vcc, s95, v214
	v_lshl_add_u64 v[208:209], v[208:209], 0, s[82:83]
	s_nop 0
	v_addc_co_u32_e32 v245, vcc, 0, v215, vcc
	v_lshl_add_u64 v[210:211], v[210:211], 0, s[82:83]
	s_cmp_lg_u32 s8, 0
	global_load_dwordx2 v[218:219], v[216:217], off
	global_load_dwordx2 v[224:225], v[244:245], off offset:1024
	v_add_co_u32_e32 v246, vcc, s0, v214
	s_nop 1
	v_addc_co_u32_e32 v247, vcc, 0, v215, vcc
	global_load_dwordx2 v[254:255], v[246:247], off offset:2048
	v_add_co_u32_e32 v246, vcc, s96, v214
	s_nop 1
	v_addc_co_u32_e32 v247, vcc, 0, v215, vcc
	global_load_dword v223, v[246:247], off offset:3072
	global_load_dword v226, v[246:247], off offset:3076
	s_waitcnt vmcnt(6)
	v_mfma_f32_16x16x32_bf16 v[146:149], v[2:5], v[138:141], 0
	s_waitcnt vmcnt(5)
	v_mfma_f32_16x16x32_bf16 v[146:149], v[6:9], v[142:145], v[146:149]
	s_nop 7
	ds_write_b128 v238, v[146:149]
	v_mfma_f32_16x16x32_bf16 v[146:149], v[10:13], v[138:141], 0
	v_mfma_f32_16x16x32_bf16 v[146:149], v[14:17], v[142:145], v[146:149]
	s_nop 7
	ds_write_b128 v238, v[146:149] offset:64
	v_mfma_f32_16x16x32_bf16 v[146:149], v[18:21], v[138:141], 0
	v_mfma_f32_16x16x32_bf16 v[146:149], v[22:25], v[142:145], v[146:149]
	s_nop 7
	ds_write_b128 v238, v[146:149] offset:128
	v_mfma_f32_16x16x32_bf16 v[146:149], v[26:29], v[138:141], 0
	v_mfma_f32_16x16x32_bf16 v[146:149], v[30:33], v[142:145], v[146:149]
	s_nop 7
	ds_write_b128 v238, v[146:149] offset:192
	v_mfma_f32_16x16x32_bf16 v[146:149], v[34:37], v[138:141], 0
	v_mfma_f32_16x16x32_bf16 v[146:149], v[38:41], v[142:145], v[146:149]
	s_nop 7
	ds_write_b128 v238, v[146:149] offset:256
	v_mfma_f32_16x16x32_bf16 v[146:149], v[42:45], v[138:141], 0
	v_mfma_f32_16x16x32_bf16 v[146:149], v[46:49], v[142:145], v[146:149]
	s_nop 7
	ds_write_b128 v238, v[146:149] offset:320
	v_mfma_f32_16x16x32_bf16 v[146:149], v[50:53], v[138:141], 0
	v_mfma_f32_16x16x32_bf16 v[146:149], v[54:57], v[142:145], v[146:149]
	s_nop 7
	ds_write_b128 v238, v[146:149] offset:384
	v_mfma_f32_16x16x32_bf16 v[146:149], v[58:61], v[138:141], 0
	v_mfma_f32_16x16x32_bf16 v[146:149], v[62:65], v[142:145], v[146:149]
	s_nop 7
	ds_write_b128 v238, v[146:149] offset:448
	s_waitcnt lgkmcnt(0)
	ds_read2st64_b64 v[146:149], v241 offset1:1
	s_waitcnt lgkmcnt(0)
	v_pk_add_f32 v[134:135], v[134:135], v[146:147] op_sel:[0,1] op_sel_hi:[1,0]
	v_pk_add_f32 v[136:137], v[136:137], v[146:147]
	s_nop 0
	v_cvt_pk_bf16_f32 v146, v136, v134
	v_pk_mul_f32 v[134:135], v[200:201], v[134:135] op_sel_hi:[1,0]
	ds_write2st64_b32 v239, v151, v146 offset0:32 offset1:33
	v_pk_fma_f32 v[146:147], v[196:197], v[136:137], v[134:135] neg_lo:[0,0,1] neg_hi:[0,0,1]
	v_pk_fma_f32 v[134:135], v[196:197], v[136:137], v[134:135] op_sel_hi:[1,0,1]
	s_nop 0
	v_mov_b32_e32 v147, v135
	ds_read2st64_b64 v[134:137], v241 offset0:2 offset1:3
	v_pk_add_f32 v[146:147], v[146:147], v[148:149]
	s_nop 0
	v_mul_f32_e32 v148, v197, v147
	v_mul_f32_e32 v150, v197, v146
	v_cvt_pk_bf16_f32 v151, v146, v147
	v_pk_fma_f32 v[148:149], v[196:197], v[146:147], v[148:149] op_sel_hi:[1,1,0] neg_lo:[0,0,1] neg_hi:[0,0,1]
	v_pk_fma_f32 v[146:147], v[196:197], v[146:147], v[150:151] op_sel:[0,1,0] op_sel_hi:[1,0,0]
	s_waitcnt lgkmcnt(0)
	v_pk_add_f32 v[148:149], v[148:149], v[134:135]
	v_pk_add_f32 v[134:135], v[146:147], v[134:135] op_sel:[0,1] op_sel_hi:[1,0]
	s_nop 0
	v_cvt_pk_bf16_f32 v146, v148, v134
	v_pk_mul_f32 v[134:135], v[200:201], v[134:135] op_sel_hi:[1,0]
	ds_write2st64_b32 v239, v151, v146 offset0:34 offset1:35
	v_pk_fma_f32 v[146:147], v[196:197], v[148:149], v[134:135] neg_lo:[0,0,1] neg_hi:[0,0,1]
	v_pk_fma_f32 v[134:135], v[196:197], v[148:149], v[134:135] op_sel_hi:[1,0,1]
	s_nop 0
	v_mov_b32_e32 v147, v135
	v_pk_add_f32 v[146:147], v[146:147], v[136:137]
	ds_read2st64_b64 v[134:137], v241 offset0:4 offset1:5
	v_mul_f32_e32 v148, v197, v147
	v_mul_f32_e32 v150, v197, v146
	v_cvt_pk_bf16_f32 v151, v146, v147
	v_pk_fma_f32 v[148:149], v[196:197], v[146:147], v[148:149] op_sel_hi:[1,1,0] neg_lo:[0,0,1] neg_hi:[0,0,1]
	v_pk_fma_f32 v[146:147], v[196:197], v[146:147], v[150:151] op_sel:[0,1,0] op_sel_hi:[1,0,0]
	s_waitcnt lgkmcnt(0)
	v_pk_add_f32 v[148:149], v[148:149], v[134:135]
	v_pk_add_f32 v[134:135], v[146:147], v[134:135] op_sel:[0,1] op_sel_hi:[1,0]
	s_nop 0
	v_cvt_pk_bf16_f32 v146, v148, v134
	v_pk_mul_f32 v[134:135], v[200:201], v[134:135] op_sel_hi:[1,0]
	ds_write2st64_b32 v239, v151, v146 offset0:36 offset1:37
	v_pk_fma_f32 v[146:147], v[196:197], v[148:149], v[134:135] neg_lo:[0,0,1] neg_hi:[0,0,1]
	v_pk_fma_f32 v[134:135], v[196:197], v[148:149], v[134:135] op_sel_hi:[1,0,1]
	s_nop 0
	v_mov_b32_e32 v147, v135
	v_pk_add_f32 v[146:147], v[146:147], v[136:137]
	ds_read2st64_b64 v[134:137], v241 offset0:6 offset1:7
	v_mul_f32_e32 v148, v197, v147
	v_mul_f32_e32 v150, v197, v146
	v_cvt_pk_bf16_f32 v151, v146, v147
	v_pk_fma_f32 v[148:149], v[196:197], v[146:147], v[148:149] op_sel_hi:[1,1,0] neg_lo:[0,0,1] neg_hi:[0,0,1]
	v_pk_fma_f32 v[146:147], v[196:197], v[146:147], v[150:151] op_sel:[0,1,0] op_sel_hi:[1,0,0]
	s_waitcnt lgkmcnt(0)
; #define LAS __attribute__((address_space(3)))
; __device__ __forceinline__ unsigned pk2(float lo, float hi) { unsigned r; asm("v_cvt_pk_bf16_f32 %0, %1, %2" : "=v"(r) : "v"(lo), "v"(hi)); return r; }
; __device__ __forceinline__ void lds_fence() { asm volatile("s_waitcnt lgkmcnt(0)" ::: "memory"); }
; __device__ __forceinline__ f32x4 mfma16(bf16x8 a, bf16x8 b, f32x4 c) { return __builtin_amdgcn_mfma_f32_16x16x32_bf16(a, b, c, 0, 0, 0); }
; template <int PASS>
; __device__ __forceinline__ void s5_pass(CArgs& a, LAS unsigned char* lds, int l, int panel) {
;     ...
;             for (int j = 0; j < 16; ++j) {
;                 if (PASS == 2) *(LAS unsigned*)(xh + j * 128 + 2 * lane) = pk2(Hr, Hi);
;                 const f32x2 lc = *(LAS f32x2*)(hl + j * 128 + 2 * lane);
;                 const float nr = a4r * Hr - a4i * Hi + lc.x, ni = a4r * Hi + a4i * Hr + lc.y;
;                 Hr = nr; Hi = ni;
;             }
;             lds_fence();
;             if (PASS == 2) {
;                 bf16x8 xhf[4];
; #pragma unroll
;                 for (int k4 = 0; k4 < 4; ++k4) xhf[k4] = *(const LAS bf16x8*)(xh + fr * 128 + 32 * k4 + 8 * fq);
; #pragma unroll
;                 for (int mt = 0; mt < 4; ++mt) {
;                     f32x4 acc = (f32x4){0.f, 0.f, 0.f, 0.f};
; #pragma unroll
;                     for (int ks = 0; ks < 2; ++ks) if (2 * ks <= mt) acc = mfma16(*(const bf16x8*)(Mg + (size_t)(16 * mt + fr) * 192 + 32 * ks + 8 * fq), xf[ks], acc);
; #pragma unroll
;                     for (int k4 = 0; k4 < 4; ++k4) acc = mfma16(mf[mt][k4], xhf[k4], acc);
;                     const int tok = (16 * nt + fr) * 4 + mt, ch = g * 16 + 4 * fq;
;                     const u32x2 uv = *(const u32x2*)(Zp + (size_t)tok * ZROWB + (C_S5U + ch) * 2);
	v_pk_add_f32 v[148:149], v[148:149], v[134:135]
	v_pk_add_f32 v[134:135], v[146:147], v[134:135] op_sel:[0,1] op_sel_hi:[1,0]
	s_nop 0
	v_cvt_pk_bf16_f32 v146, v148, v134
	v_pk_mul_f32 v[134:135], v[200:201], v[134:135] op_sel_hi:[1,0]
	ds_write2st64_b32 v239, v151, v146 offset0:38 offset1:39
	v_pk_fma_f32 v[146:147], v[196:197], v[148:149], v[134:135] neg_lo:[0,0,1] neg_hi:[0,0,1]
	v_pk_fma_f32 v[134:135], v[196:197], v[148:149], v[134:135] op_sel_hi:[1,0,1]
	s_nop 0
	v_mov_b32_e32 v147, v135
	v_pk_add_f32 v[146:147], v[146:147], v[136:137]
	ds_read2st64_b64 v[134:137], v241 offset0:8 offset1:9
	v_mul_f32_e32 v148, v197, v147
	v_mul_f32_e32 v150, v197, v146
	v_cvt_pk_bf16_f32 v151, v146, v147
	v_pk_fma_f32 v[148:149], v[196:197], v[146:147], v[148:149] op_sel_hi:[1,1,0] neg_lo:[0,0,1] neg_hi:[0,0,1]
	v_pk_fma_f32 v[146:147], v[196:197], v[146:147], v[150:151] op_sel:[0,1,0] op_sel_hi:[1,0,0]
	s_waitcnt lgkmcnt(0)
	v_pk_add_f32 v[148:149], v[148:149], v[134:135]
	v_pk_add_f32 v[134:135], v[146:147], v[134:135] op_sel:[0,1] op_sel_hi:[1,0]
	s_nop 0
	v_cvt_pk_bf16_f32 v146, v148, v134
	v_pk_mul_f32 v[134:135], v[200:201], v[134:135] op_sel_hi:[1,0]
	ds_write2st64_b32 v239, v151, v146 offset0:40 offset1:41
	v_pk_fma_f32 v[146:147], v[196:197], v[148:149], v[134:135] neg_lo:[0,0,1] neg_hi:[0,0,1]
	v_pk_fma_f32 v[134:135], v[196:197], v[148:149], v[134:135] op_sel_hi:[1,0,1]
	s_nop 0
	v_mov_b32_e32 v147, v135
	v_pk_add_f32 v[146:147], v[146:147], v[136:137]
	ds_read2st64_b64 v[134:137], v241 offset0:10 offset1:11
	v_mul_f32_e32 v148, v197, v147
	v_mul_f32_e32 v150, v197, v146
	v_cvt_pk_bf16_f32 v151, v146, v147
	v_pk_fma_f32 v[148:149], v[196:197], v[146:147], v[148:149] op_sel_hi:[1,1,0] neg_lo:[0,0,1] neg_hi:[0,0,1]
	v_pk_fma_f32 v[146:147], v[196:197], v[146:147], v[150:151] op_sel:[0,1,0] op_sel_hi:[1,0,0]
	s_waitcnt lgkmcnt(0)
	v_pk_add_f32 v[148:149], v[148:149], v[134:135]
	v_pk_add_f32 v[134:135], v[146:147], v[134:135] op_sel:[0,1] op_sel_hi:[1,0]
	s_nop 0
	v_cvt_pk_bf16_f32 v146, v148, v134
	v_pk_mul_f32 v[134:135], v[196:197], v[134:135] op_sel_hi:[1,0]
	ds_write2st64_b32 v239, v151, v146 offset0:42 offset1:43
	v_pk_fma_f32 v[146:147], v[200:201], v[148:149], v[134:135]
	v_pk_fma_f32 v[134:135], v[200:201], v[148:149], v[134:135] op_sel_hi:[1,0,1] neg_lo:[0,0,1] neg_hi:[0,0,1]
	s_nop 0
	v_mov_b32_e32 v147, v135
	v_pk_add_f32 v[146:147], v[146:147], v[136:137] op_sel:[0,1] op_sel_hi:[1,0]
	ds_read2st64_b64 v[134:137], v241 offset0:12 offset1:13
	v_mul_f32_e32 v148, v197, v146
	v_mul_f32_e32 v150, v197, v147
	v_cvt_pk_bf16_f32 v151, v147, v146
	v_pk_fma_f32 v[148:149], v[196:197], v[146:147], v[148:149] op_sel:[0,1,0] op_sel_hi:[1,0,0] neg_lo:[0,0,1] neg_hi:[0,0,1]
	v_pk_fma_f32 v[146:147], v[196:197], v[146:147], v[150:151] op_sel_hi:[1,1,0]
	s_waitcnt lgkmcnt(0)
	v_pk_add_f32 v[148:149], v[148:149], v[134:135]
	v_pk_add_f32 v[134:135], v[146:147], v[134:135] op_sel:[0,1] op_sel_hi:[1,0]
	s_nop 0
	v_cvt_pk_bf16_f32 v146, v148, v134
	v_pk_mul_f32 v[134:135], v[196:197], v[134:135] op_sel_hi:[1,0]
	ds_write2st64_b32 v239, v151, v146 offset0:44 offset1:45
	v_pk_fma_f32 v[146:147], v[200:201], v[148:149], v[134:135]
	v_pk_fma_f32 v[134:135], v[200:201], v[148:149], v[134:135] op_sel_hi:[1,0,1] neg_lo:[0,0,1] neg_hi:[0,0,1]
	s_nop 0
	v_mov_b32_e32 v147, v135
	v_pk_add_f32 v[146:147], v[146:147], v[136:137] op_sel:[0,1] op_sel_hi:[1,0]
	ds_read2st64_b64 v[134:137], v241 offset0:14 offset1:15
	v_mul_f32_e32 v148, v197, v146
	v_pk_fma_f32 v[148:149], v[196:197], v[146:147], v[148:149] op_sel:[0,1,0] op_sel_hi:[1,0,0] neg_lo:[0,0,1] neg_hi:[0,0,1]
	v_cvt_pk_bf16_f32 v150, v147, v146
	s_waitcnt lgkmcnt(0)
	v_pk_add_f32 v[162:163], v[148:149], v[134:135]
	v_mul_f32_e32 v148, v197, v147
	v_pk_fma_f32 v[146:147], v[196:197], v[146:147], v[148:149] op_sel_hi:[1,1,0]
	s_nop 0
	v_pk_add_f32 v[134:135], v[146:147], v[134:135] op_sel:[0,1] op_sel_hi:[1,0]
	s_nop 0
	v_cvt_pk_bf16_f32 v146, v162, v134
	ds_write2st64_b32 v239, v150, v146 offset0:46 offset1:47
	v_pk_mul_f32 v[164:165], v[200:201], v[134:135] op_sel_hi:[1,0]
	s_waitcnt lgkmcnt(0)
	ds_read_b128 v[146:149], v240 offset:8192
	ds_read_b128 v[150:153], v240 offset:8256
	ds_read_b128 v[154:157], v240 offset:8320
	ds_read_b128 v[158:161], v240 offset:8384
	v_pk_fma_f32 v[134:135], v[196:197], v[162:163], v[164:165] neg_lo:[0,0,1] neg_hi:[0,0,1]
	v_pk_fma_f32 v[162:163], v[196:197], v[162:163], v[164:165] op_sel_hi:[1,0,1]
	v_mov_b32_e32 v135, v163
	ds_read_b128 v[162:165], v220
	s_waitcnt vmcnt(0) lgkmcnt(0)
	v_mfma_f32_16x16x32_bf16 v[162:165], v[162:165], v[138:141], 0
	v_lshlrev_b32_e32 v177, 16, v218
	v_pk_add_f32 v[134:135], v[134:135], v[136:137]
	s_waitcnt lgkmcnt(3)
	v_mfma_f32_16x16x32_bf16 v[162:165], v[66:69], v[146:149], v[162:165]
	s_waitcnt lgkmcnt(2)
	v_mfma_f32_16x16x32_bf16 v[162:165], v[70:73], v[150:153], v[162:165]
	s_waitcnt lgkmcnt(1)
	v_mfma_f32_16x16x32_bf16 v[162:165], v[74:77], v[154:157], v[162:165]
	s_waitcnt lgkmcnt(0)
; __device__ __forceinline__ unsigned pk2(float lo, float hi) { unsigned r; asm("v_cvt_pk_bf16_f32 %0, %1, %2" : "=v"(r) : "v"(lo), "v"(hi)); return r; }
; __device__ __forceinline__ float bflo(unsigned w) { return __uint_as_float(w << 16); }
; __device__ __forceinline__ float bfhi(unsigned w) { return __uint_as_float(w & 0xffff0000u); }
; __device__ __forceinline__ float gelu_tanh(float x) { const float u = 0.7978845608028654f * (x + 0.044715f * x * x * x); return x * __builtin_amdgcn_rcpf(1.f + fexp(-2.f * u)); }
; __device__ __forceinline__ f32x4 mfma16(bf16x8 a, bf16x8 b, f32x4 c) { return __builtin_amdgcn_mfma_f32_16x16x32_bf16(a, b, c, 0, 0, 0); }
; template <int PASS>
; __device__ __forceinline__ void s5_pass(CArgs& a, LAS unsigned char* lds, int l, int panel) {
;     ...
;                 for (int mt = 0; mt < 4; ++mt) {
;                     f32x4 acc = (f32x4){0.f, 0.f, 0.f, 0.f};
; #pragma unroll
;                     for (int ks = 0; ks < 2; ++ks) if (2 * ks <= mt) acc = mfma16(*(const bf16x8*)(Mg + (size_t)(16 * mt + fr) * 192 + 32 * ks + 8 * fq), xf[ks], acc);
; #pragma unroll
;                     for (int k4 = 0; k4 < 4; ++k4) acc = mfma16(mf[mt][k4], xhf[k4], acc);
;                     const int tok = (16 * nt + fr) * 4 + mt, ch = g * 16 + 4 * fq;
;                     const u32x2 uv = *(const u32x2*)(Zp + (size_t)tok * ZROWB + (C_S5U + ch) * 2);
;                     const float y0 = gelu_tanh(acc[0] + dsk[0] * bflo(uv.x)), y1 = gelu_tanh(acc[1] + dsk[1] * bfhi(uv.x));
;                     const float y2 = gelu_tanh(acc[2] + dsk[2] * bflo(uv.y)), y3 = gelu_tanh(acc[3] + dsk[3] * bfhi(uv.y));
;                     u32x2 w; w.x = pk2(y0, y1); w.y = pk2(y2, y3);
;                     *(u32x2*)(YS5 + (size_t)tok * 512 + ch * 2) = w;
	v_mfma_f32_16x16x32_bf16 v[162:165], v[78:81], v[158:161], v[162:165]
	s_nop 7
	v_fma_f32 v162, v130, v177, v162
	v_mul_f32_e32 v177, 0x3d372713, v162
	v_mul_f32_e32 v177, v162, v177
	v_fma_f32 v177, v162, v177, v162
	v_mul_f32_e32 v177, 0x3f4c422a, v177
	v_mul_f32_e32 v177, -2.0, v177
	v_mul_f32_e32 v177, 0x3fb8aa3b, v177
	v_exp_f32_e32 v177, v177
	s_nop 0
	v_add_f32_e32 v177, 1.0, v177
	v_rcp_f32_e32 v177, v177
	s_nop 0
	v_mul_f32_e32 v162, v162, v177
	v_and_b32_e32 v177, 0xffff0000, v218
	v_fma_f32 v163, v131, v177, v163
	v_mul_f32_e32 v177, 0x3d372713, v163
	v_mul_f32_e32 v177, v163, v177
	v_fma_f32 v177, v163, v177, v163
	v_mul_f32_e32 v177, 0x3f4c422a, v177
	v_mul_f32_e32 v177, -2.0, v177
	v_mul_f32_e32 v177, 0x3fb8aa3b, v177
	v_exp_f32_e32 v177, v177
	s_nop 0
	v_add_f32_e32 v177, 1.0, v177
	v_rcp_f32_e32 v177, v177
	s_nop 0
	v_mul_f32_e32 v163, v163, v177
	v_lshlrev_b32_e32 v177, 16, v219
	v_fma_f32 v164, v132, v177, v164
	v_mul_f32_e32 v177, 0x3d372713, v164
	v_mul_f32_e32 v177, v164, v177
	v_fma_f32 v177, v164, v177, v164
	v_mul_f32_e32 v177, 0x3f4c422a, v177
	v_mul_f32_e32 v177, -2.0, v177
	v_mul_f32_e32 v177, 0x3fb8aa3b, v177
	v_exp_f32_e32 v177, v177
	v_cvt_pk_bf16_f32 v162, v162, v163
	s_nop 0
	v_add_f32_e32 v177, 1.0, v177
	v_rcp_f32_e32 v177, v177
	s_nop 0
	v_mul_f32_e32 v164, v164, v177
	v_and_b32_e32 v177, 0xffff0000, v219
	v_fmac_f32_e32 v165, v133, v177
	v_mul_f32_e32 v177, 0x3d372713, v165
	v_mul_f32_e32 v177, v165, v177
	v_fma_f32 v177, v165, v177, v165
	v_mul_f32_e32 v177, 0x3f4c422a, v177
	v_mul_f32_e32 v177, -2.0, v177
	v_mul_f32_e32 v177, 0x3fb8aa3b, v177
	v_exp_f32_e32 v177, v177
	v_lshl_add_u64 v[216:217], v[212:213], 0, s[88:89]
	v_lshl_add_u64 v[212:213], v[212:213], 0, s[14:15]
	v_add_f32_e32 v177, 1.0, v177
	v_rcp_f32_e32 v177, v177
	s_nop 0
	v_mul_f32_e32 v165, v165, v177
	v_cvt_pk_bf16_f32 v163, v164, v165
	global_store_dwordx2 v[216:217], v[162:163], off offset:-1024
	v_mfma_f32_16x16x32_bf16 v[162:165], v[250:253], v[138:141], 0
	v_lshlrev_b32_e32 v177, 16, v224
	v_mfma_f32_16x16x32_bf16 v[162:165], v[82:85], v[146:149], v[162:165]
	v_mfma_f32_16x16x32_bf16 v[162:165], v[86:89], v[150:153], v[162:165]
	v_mfma_f32_16x16x32_bf16 v[162:165], v[90:93], v[154:157], v[162:165]
	v_mfma_f32_16x16x32_bf16 v[162:165], v[94:97], v[158:161], v[162:165]
	s_nop 7
	v_fma_f32 v162, v130, v177, v162
	v_mul_f32_e32 v177, 0x3d372713, v162
	v_mul_f32_e32 v177, v162, v177
	v_fma_f32 v177, v162, v177, v162
	v_mul_f32_e32 v177, 0x3f4c422a, v177
	v_mul_f32_e32 v177, -2.0, v177
	v_mul_f32_e32 v177, 0x3fb8aa3b, v177
	v_exp_f32_e32 v177, v177
	s_nop 0
	v_add_f32_e32 v177, 1.0, v177
	v_rcp_f32_e32 v177, v177
	s_nop 0
	v_mul_f32_e32 v162, v162, v177
	v_and_b32_e32 v177, 0xffff0000, v224
	v_fma_f32 v163, v131, v177, v163
	v_mul_f32_e32 v177, 0x3d372713, v163
	v_mul_f32_e32 v177, v163, v177
	v_fma_f32 v177, v163, v177, v163
	v_mul_f32_e32 v177, 0x3f4c422a, v177
	v_mul_f32_e32 v177, -2.0, v177
	v_mul_f32_e32 v177, 0x3fb8aa3b, v177
	v_exp_f32_e32 v177, v177
	s_nop 0
	v_add_f32_e32 v177, 1.0, v177
	v_rcp_f32_e32 v177, v177
	s_nop 0
	v_mul_f32_e32 v163, v163, v177
	v_lshlrev_b32_e32 v177, 16, v225
	v_fma_f32 v164, v132, v177, v164
	v_mul_f32_e32 v177, 0x3d372713, v164
	v_mul_f32_e32 v177, v164, v177
	v_fma_f32 v177, v164, v177, v164
	v_mul_f32_e32 v177, 0x3f4c422a, v177
	v_mul_f32_e32 v177, -2.0, v177
	v_mul_f32_e32 v177, 0x3fb8aa3b, v177
	v_exp_f32_e32 v177, v177
	v_cvt_pk_bf16_f32 v162, v162, v163
	s_nop 0
	v_add_f32_e32 v177, 1.0, v177
	v_rcp_f32_e32 v177, v177
	s_nop 0
	v_mul_f32_e32 v164, v164, v177
	v_and_b32_e32 v177, 0xffff0000, v225
	v_fmac_f32_e32 v165, v133, v177
	v_mul_f32_e32 v177, 0x3d372713, v165
	v_mul_f32_e32 v177, v165, v177
	v_fma_f32 v177, v165, v177, v165
	v_mul_f32_e32 v177, 0x3f4c422a, v177
	v_mul_f32_e32 v177, -2.0, v177
	v_mul_f32_e32 v177, 0x3fb8aa3b, v177
	v_exp_f32_e32 v177, v177
	s_nop 0
	v_add_f32_e32 v177, 1.0, v177
	v_rcp_f32_e32 v177, v177
	s_nop 0
	v_mul_f32_e32 v165, v165, v177
	v_cvt_pk_bf16_f32 v163, v164, v165
	global_store_dwordx2 v[216:217], v[162:163], off offset:-512
	ds_read_b128 v[162:165], v191
	s_nop 0
	ds_read_b128 v[244:247], v191 offset:8192
	s_waitcnt lgkmcnt(1)
	v_mfma_f32_16x16x32_bf16 v[162:165], v[162:165], v[138:141], 0
	s_waitcnt lgkmcnt(0)
	v_mfma_f32_16x16x32_bf16 v[162:165], v[244:247], v[142:145], v[162:165]
	v_mfma_f32_16x16x32_bf16 v[162:165], v[98:101], v[146:149], v[162:165]
	v_lshlrev_b32_e32 v177, 16, v254
	v_mfma_f32_16x16x32_bf16 v[162:165], v[102:105], v[150:153], v[162:165]
	v_mfma_f32_16x16x32_bf16 v[162:165], v[106:109], v[154:157], v[162:165]
	v_mfma_f32_16x16x32_bf16 v[162:165], v[110:113], v[158:161], v[162:165]
	s_nop 7
	v_fma_f32 v162, v130, v177, v162
	v_mul_f32_e32 v177, 0x3d372713, v162
	v_mul_f32_e32 v177, v162, v177
	v_fma_f32 v177, v162, v177, v162
	v_mul_f32_e32 v177, 0x3f4c422a, v177
	v_mul_f32_e32 v177, -2.0, v177
	v_mul_f32_e32 v177, 0x3fb8aa3b, v177
	v_exp_f32_e32 v177, v177
	s_nop 0
	v_add_f32_e32 v177, 1.0, v177
	v_rcp_f32_e32 v177, v177
	s_nop 0
	v_mul_f32_e32 v162, v162, v177
	v_and_b32_e32 v177, 0xffff0000, v254
	v_fma_f32 v163, v131, v177, v163
	v_mul_f32_e32 v177, 0x3d372713, v163
	v_mul_f32_e32 v177, v163, v177
	v_fma_f32 v177, v163, v177, v163
	v_mul_f32_e32 v177, 0x3f4c422a, v177
	v_mul_f32_e32 v177, -2.0, v177
	v_mul_f32_e32 v177, 0x3fb8aa3b, v177
	v_exp_f32_e32 v177, v177
	s_nop 0
	v_add_f32_e32 v177, 1.0, v177
	v_rcp_f32_e32 v177, v177
	s_nop 0
	v_mul_f32_e32 v163, v163, v177
	v_lshlrev_b32_e32 v177, 16, v255
	v_fma_f32 v164, v132, v177, v164
	v_mul_f32_e32 v177, 0x3d372713, v164
	v_mul_f32_e32 v177, v164, v177
	v_fma_f32 v177, v164, v177, v164
	v_mul_f32_e32 v177, 0x3f4c422a, v177
	v_mul_f32_e32 v177, -2.0, v177
	v_mul_f32_e32 v177, 0x3fb8aa3b, v177
	v_exp_f32_e32 v177, v177
	v_cvt_pk_bf16_f32 v162, v162, v163
	s_nop 0
	v_add_f32_e32 v177, 1.0, v177
	v_rcp_f32_e32 v177, v177
	s_nop 0
	v_mul_f32_e32 v164, v164, v177
	v_and_b32_e32 v177, 0xffff0000, v255
	v_fmac_f32_e32 v165, v133, v177
	v_mul_f32_e32 v177, 0x3d372713, v165
	v_mul_f32_e32 v177, v165, v177
	v_fma_f32 v177, v165, v177, v165
	v_mul_f32_e32 v177, 0x3f4c422a, v177
	v_mul_f32_e32 v177, -2.0, v177
	v_mul_f32_e32 v177, 0x3fb8aa3b, v177
	v_exp_f32_e32 v177, v177
	s_nop 0
	v_add_f32_e32 v177, 1.0, v177
	v_rcp_f32_e32 v177, v177
	s_nop 0
	v_mul_f32_e32 v165, v165, v177
	v_cvt_pk_bf16_f32 v163, v164, v165
	global_store_dwordx2 v[216:217], v[162:163], off
	ds_read_b128 v[162:165], v191 offset:16384
	s_waitcnt lgkmcnt(0)
; __device__ __forceinline__ float bflo(unsigned w) { return __uint_as_float(w << 16); }
; template <int PASS>
; __device__ __forceinline__ void s5_pass(CArgs& a, LAS unsigned char* lds, int l, int panel) {
;     ...
;         const int g = 2 * wave + gi;
;         const bf16_t* Wg = (const bf16_t*)(ws + WS_S5W) + (size_t)(l * 16 + g) * 128 * 64;
;         const bf16_t* Mg = (const bf16_t*)(ws + WS_S5M) + (size_t)(l * 16 + g) * 64 * 192;
;         bf16x8 wf[8][2];
; #pragma unroll
;         for (int mt = 0; mt < 8; ++mt)
; #pragma unroll
;             for (int ks = 0; ks < 2; ++ks) wf[mt][ks] = *(const bf16x8*)(Wg + (size_t)(16 * mt + fr) * 64 + 32 * ks + 8 * fq);
;         bf16x8 mf[4][4];
;         f32x4 dsk = (f32x4){0.f, 0.f, 0.f, 0.f};
;         if (PASS == 2) {
; #pragma unroll
;             for (int mt = 0; mt < 4; ++mt)
; #pragma unroll
;                 for (int ks = 0; ks < 4; ++ks) mf[mt][ks] = *(const bf16x8*)(Mg + (size_t)(16 * mt + fr) * 192 + 64 + 32 * ks + 8 * fq);
;             dsk = *(const f32x4*)(a.in[11] + l * 256 + g * 16 + 4 * fq);
;         }
;         const float* Ap = (const float*)(ws + WS_S5A) + ((size_t)(l * 16 + g) * 64 + lane) * 4;
;         const float a4r = Ap[0], a4i = Ap[1];
;         float* Hg = (float*)(ws + WS_S5H) + ((size_t)panel * 16 + g) * 128 + 2 * lane;
;         float Hr = 0.f, Hi = 0.f;
;         if (PASS == 2) { Hr = Hg[0]; Hi = Hg[1]; }
;     ...
;                     for (int ks = 0; ks < 2; ++ks) if (2 * ks <= mt) acc = mfma16(*(const bf16x8*)(Mg + (size_t)(16 * mt + fr) * 192 + 32 * ks + 8 * fq), xf[ks], acc);
; #pragma unroll
;                     for (int k4 = 0; k4 < 4; ++k4) acc = mfma16(mf[mt][k4], xhf[k4], acc);
;                     const int tok = (16 * nt + fr) * 4 + mt, ch = g * 16 + 4 * fq;
;                     const u32x2 uv = *(const u32x2*)(Zp + (size_t)tok * ZROWB + (C_S5U + ch) * 2);
;                     const float y0 = gelu_tanh(acc[0] + dsk[0] * bflo(uv.x)), y1 = gelu_tanh(acc[1] + dsk[1] * bfhi(uv.x));
;                     const float y2 = gelu_tanh(acc[2] + dsk[2] * bflo(uv.y)), y3 = gelu_tanh(acc[3] + dsk[3] * bfhi(uv.y));
;                     u32x2 w; w.x = pk2(y0, y1); w.y = pk2(y2, y3);
;                     *(u32x2*)(YS5 + (size_t)tok * 512 + ch * 2) = w;
;                 }
;             }
;             lds_fence();
;         }
;         if (PASS == 1) { Hg[0] = Hr; Hg[1] = Hi; }
	v_mfma_f32_16x16x32_bf16 v[138:141], v[162:165], v[138:141], 0
	ds_read_b128 v[162:165], v191 offset:24576
	s_waitcnt lgkmcnt(0)
	v_mfma_f32_16x16x32_bf16 v[138:141], v[162:165], v[142:145], v[138:141]
	v_mfma_f32_16x16x32_bf16 v[138:141], v[114:117], v[146:149], v[138:141]
	v_lshlrev_b32_e32 v144, 16, v223
	v_mfma_f32_16x16x32_bf16 v[138:141], v[118:121], v[150:153], v[138:141]
	v_and_b32_e32 v142, 0xffff0000, v223
	v_mfma_f32_16x16x32_bf16 v[138:141], v[122:125], v[154:157], v[138:141]
	v_mfma_f32_16x16x32_bf16 v[138:141], v[126:129], v[158:161], v[138:141]
	s_nop 7
	v_fma_f32 v139, v131, v142, v139
	v_mul_f32_e32 v142, 0x3d372713, v139
	v_mul_f32_e32 v142, v139, v142
	v_fma_f32 v142, v139, v142, v139
	v_mul_f32_e32 v142, 0x3f4c422a, v142
	v_mul_f32_e32 v142, -2.0, v142
	v_mul_f32_e32 v142, 0x3fb8aa3b, v142
	v_exp_f32_e32 v142, v142
	v_fma_f32 v138, v130, v144, v138
	v_mul_f32_e32 v144, 0x3d372713, v138
	v_mul_f32_e32 v144, v138, v144
	v_add_f32_e32 v142, 1.0, v142
	v_rcp_f32_e32 v142, v142
	v_fma_f32 v144, v138, v144, v138
	v_mul_f32_e32 v144, 0x3f4c422a, v144
	v_mul_f32_e32 v144, -2.0, v144
	v_mul_f32_e32 v139, v139, v142
	v_lshlrev_b32_e32 v142, 16, v226
	v_fma_f32 v140, v132, v142, v140
	v_mul_f32_e32 v142, 0x3d372713, v140
	v_mul_f32_e32 v142, v140, v142
	v_fma_f32 v142, v140, v142, v140
	v_mul_f32_e32 v142, 0x3f4c422a, v142
	v_mul_f32_e32 v142, -2.0, v142
	v_mul_f32_e32 v142, 0x3fb8aa3b, v142
	v_exp_f32_e32 v142, v142
	v_mul_f32_e32 v144, 0x3fb8aa3b, v144
	v_exp_f32_e32 v144, v144
	v_add_f32_e32 v142, 1.0, v142
	v_rcp_f32_e32 v142, v142
	v_add_f32_e32 v144, 1.0, v144
	v_rcp_f32_e32 v144, v144
	v_mul_f32_e32 v140, v140, v142
	v_and_b32_e32 v142, 0xffff0000, v226
	v_fmac_f32_e32 v141, v133, v142
	v_mul_f32_e32 v142, 0x3d372713, v141
	v_mul_f32_e32 v142, v141, v142
	v_fma_f32 v142, v141, v142, v141
	v_mul_f32_e32 v142, 0x3f4c422a, v142
	v_mul_f32_e32 v142, -2.0, v142
	v_mul_f32_e32 v142, 0x3fb8aa3b, v142
	v_exp_f32_e32 v142, v142
	v_mul_f32_e32 v138, v138, v144
	v_cvt_pk_bf16_f32 v138, v138, v139
	v_add_f32_e32 v142, 1.0, v142
	v_rcp_f32_e32 v142, v142
	s_nop 0
	v_mul_f32_e32 v141, v141, v142
	v_cvt_pk_bf16_f32 v139, v140, v141
	global_store_dwordx2 v[216:217], v[138:139], off offset:512
	s_waitcnt lgkmcnt(0)
	s_cbranch_scc1 .LBB0_363
	s_or_b32 s10, s10, 1
	s_add_i32 s8, s10, s66
	s_ashr_i32 s9, s8, 31
	s_lshl_b64 s[18:19], s[8:9], 14
	s_mul_i32 s11, s8, 0x6000
	s_mul_hi_i32 s1, s8, 0x6000
	v_lshl_add_u64 v[58:59], v[174:175], 0, s[18:19]
	s_add_u32 s18, s4, s11
	s_addc_u32 s19, s5, s1
	v_lshlrev_b32_e32 v136, 1, v188
	v_mov_b32_e32 v137, v1
	v_lshl_add_u64 v[66:67], s[18:19], 0, v[136:137]
	v_lshlrev_b32_e32 v138, 1, v190
	v_mov_b32_e32 v139, v1
	v_lshl_add_u64 v[114:115], v[66:67], 0, v[138:139]
	s_mov_b64 s[4:5], 0x3000
	v_lshlrev_b32_e32 v2, 1, v172
	v_mov_b32_e32 v3, v1
	v_lshlrev_b32_e32 v18, 1, v176
	v_mov_b32_e32 v19, v1
	v_lshlrev_b32_e32 v26, 1, v178
	v_mov_b32_e32 v27, v1
	v_lshlrev_b32_e32 v34, 1, v180
	v_mov_b32_e32 v35, v1
	v_lshlrev_b32_e32 v42, 1, v182
	v_mov_b32_e32 v43, v1
	v_lshlrev_b32_e32 v50, 1, v184
	v_mov_b32_e32 v51, v1
	v_lshlrev_b32_e32 v60, 1, v186
	v_mov_b32_e32 v61, v1
	s_mov_b64 s[40:41], 0x1800
	v_lshl_add_u64 v[172:173], v[114:115], 0, s[4:5]
	s_lshl_b64 s[4:5], s[8:9], 10
	s_lshl_b32 s8, s10, 4
	s_ashr_i32 s11, s10, 31
	v_lshl_add_u64 v[14:15], v[58:59], 0, v[2:3]
	v_lshl_add_u64 v[22:23], v[58:59], 0, v[18:19]
	v_lshl_add_u64 v[30:31], v[58:59], 0, v[26:27]
	v_lshl_add_u64 v[38:39], v[58:59], 0, v[34:35]
	v_lshl_add_u64 v[46:47], v[58:59], 0, v[42:43]
	v_lshl_add_u64 v[54:55], v[58:59], 0, v[50:51]
	v_lshl_add_u64 v[62:63], v[58:59], 0, v[60:61]
	v_lshl_add_u64 v[94:95], v[114:115], 0, s[40:41]
	v_lshl_add_u64 v[116:117], v[170:171], 0, s[4:5]
	s_mov_b64 s[42:43], 0x4800
	s_ashr_i32 s9, s8, 31
	s_lshl_b64 s[4:5], s[10:11], 9
	global_load_dwordx4 v[2:5], v[14:15], off
	global_load_dwordx4 v[6:9], v[14:15], off offset:64
	global_load_dwordx4 v[10:13], v[14:15], off offset:2048
	s_nop 0
	global_load_dwordx4 v[14:17], v[14:15], off offset:2112
	s_nop 0
	global_load_dwordx4 v[18:21], v[22:23], off
	s_nop 0
	global_load_dwordx4 v[22:25], v[22:23], off offset:64
	s_nop 0
	global_load_dwordx4 v[26:29], v[30:31], off
	s_nop 0
	global_load_dwordx4 v[30:33], v[30:31], off offset:64
	s_nop 0
	global_load_dwordx4 v[34:37], v[38:39], off
	s_nop 0
	global_load_dwordx4 v[38:41], v[38:39], off offset:64
	s_nop 0
	global_load_dwordx4 v[42:45], v[46:47], off
	s_nop 0
	global_load_dwordx4 v[46:49], v[46:47], off offset:64
	s_nop 0
	global_load_dwordx4 v[50:53], v[54:55], off
	s_nop 0
	global_load_dwordx4 v[54:57], v[54:55], off offset:64
	s_nop 0
	global_load_dwordx4 v[58:61], v[62:63], off
	s_nop 0
	global_load_dwordx4 v[62:65], v[62:63], off offset:64
	s_nop 0
	global_load_dwordx4 v[66:69], v[114:115], off offset:128
	global_load_dwordx4 v[70:73], v[114:115], off offset:192
	global_load_dwordx4 v[74:77], v[114:115], off offset:256
	global_load_dwordx4 v[78:81], v[114:115], off offset:320
	global_load_dwordx4 v[82:85], v[94:95], off offset:128
	global_load_dwordx4 v[86:89], v[94:95], off offset:192
	global_load_dwordx4 v[90:93], v[94:95], off offset:256
	s_nop 0
	global_load_dwordx4 v[94:97], v[94:95], off offset:320
	s_nop 0
	global_load_dwordx4 v[98:101], v[172:173], off offset:128
	global_load_dwordx4 v[102:105], v[172:173], off offset:192
	global_load_dwordx4 v[106:109], v[172:173], off offset:256
	global_load_dwordx4 v[110:113], v[172:173], off offset:320
	v_lshl_add_u64 v[130:131], v[114:115], 0, s[42:43]
	v_lshl_add_u64 v[122:123], s[8:9], 2, v[166:167]
	v_lshl_add_u64 v[126:127], v[168:169], 0, s[4:5]
	global_load_dwordx2 v[170:171], v[116:117], off
	s_nop 0
	global_load_dwordx4 v[114:117], v[130:131], off offset:128
	global_load_dwordx4 v[118:121], v[130:131], off offset:192
	v_and_or_b32 v140, v190, 8, s8
	global_load_dwordx4 v[122:125], v[122:123], off
	s_nop 0
	global_load_dwordx2 v[134:135], v[126:127], off
	s_nop 0
	global_load_dwordx4 v[126:129], v[130:131], off offset:256
	s_nop 0
	global_load_dwordx4 v[130:133], v[130:131], off offset:320
	v_lshlrev_b32_e32 v140, 1, v140
	v_lshl_add_u64 v[138:139], s[18:19], 0, v[138:139]
	v_ashrrev_i32_e32 v141, 31, v140
	v_lshl_add_u64 v[168:169], v[138:139], 0, v[136:137]
	v_lshl_add_u64 v[136:137], v[140:141], 0, v[0:1]
	s_add_i32 s1, s26, 16
	v_lshl_add_u64 v[178:179], s[2:3], 0, v[136:137]
	v_add_lshl_u32 v136, s1, v181, 1
	v_ashrrev_i32_e32 v137, 31, v136
	v_lshl_add_u64 v[138:139], v[192:193], 0, v[136:137]
	v_lshl_add_u64 v[136:137], v[194:195], 0, v[136:137]
	s_mov_b32 s4, 4
	v_lshl_add_u64 v[174:175], v[168:169], 0, s[40:41]
	v_lshl_add_u64 v[176:177], v[168:169], 0, s[42:43]
	v_lshl_add_u64 v[180:181], s[2:3], 0, v[138:139]
	v_lshl_add_u64 v[182:183], s[38:39], 0, v[136:137]
	s_waitcnt vmcnt(6)
; #define LAS __attribute__((address_space(3)))
; __device__ __forceinline__ unsigned pk2(float lo, float hi) { unsigned r; asm("v_cvt_pk_bf16_f32 %0, %1, %2" : "=v"(r) : "v"(lo), "v"(hi)); return r; }
; __device__ __forceinline__ void lds_fence() { asm volatile("s_waitcnt lgkmcnt(0)" ::: "memory"); }
; __device__ __forceinline__ f32x4 mfma16(bf16x8 a, bf16x8 b, f32x4 c) { return __builtin_amdgcn_mfma_f32_16x16x32_bf16(a, b, c, 0, 0, 0); }
; template <int PASS>
; __device__ __forceinline__ void s5_pass(CArgs& a, LAS unsigned char* lds, int l, int panel) {
;     ...
;         for (int nt = 0; nt < 4; ++nt) {
;             bf16x8 xf[2];
; #pragma unroll
;             for (int ks = 0; ks < 2; ++ks) xf[ks] = *(const bf16x8*)(Zp + (size_t)(64 * nt + 4 * fr + 2 * ks + (fq >> 1)) * ZROWB + (C_S5U + g * 16 + (fq & 1) * 8) * 2);
; #pragma unroll
;             for (int mt = 0; mt < 8; ++mt) {
;                 f32x4 acc = mfma16(wf[mt][0], xf[0], (f32x4){0.f, 0.f, 0.f, 0.f});
;                 acc = mfma16(wf[mt][1], xf[1], acc);
;                 *(LAS f32x4*)(hl + fr * 128 + 16 * mt + 4 * fq) = acc;
;             }
;             lds_fence();
;             for (int j = 0; j < 16; ++j) {
;                 if (PASS == 2) *(LAS unsigned*)(xh + j * 128 + 2 * lane) = pk2(Hr, Hi);
;                 const f32x2 lc = *(LAS f32x2*)(hl + j * 128 + 2 * lane);
;                 const float nr = a4r * Hr - a4i * Hi + lc.x, ni = a4r * Hi + a4i * Hr + lc.y;
;                 Hr = nr; Hi = ni;
;             }
;             lds_fence();
;             if (PASS == 2) {
;                 bf16x8 xhf[4];
; #pragma unroll
;                 for (int k4 = 0; k4 < 4; ++k4) xhf[k4] = *(const LAS bf16x8*)(xh + fr * 128 + 32 * k4 + 8 * fq);
; #pragma unroll
;                 for (int mt = 0; mt < 4; ++mt) {
;                     f32x4 acc = (f32x4){0.f, 0.f, 0.f, 0.f};
; #pragma unroll
;                     for (int ks = 0; ks < 2; ++ks) if (2 * ks <= mt) acc = mfma16(*(const bf16x8*)(Mg + (size_t)(16 * mt + fr) * 192 + 32 * ks + 8 * fq), xf[ks], acc);
	v_pk_mov_b32 v[166:167], v[170:171], v[170:171] op_sel:[1,0]
	v_lshlrev_b32_e32 v191, 4, v189
	v_lshrrev_b32_e32 v223, 8, v189
	v_lshl_add_u32 v220, v223, 4, v191
	v_add_u32_e32 v220, 0x21000, v220
	v_add_u32_e32 v191, 0x18000, v191
	global_load_dwordx4 v[250:253], v[172:173], off
	global_load_dwordx4 v[162:165], v[172:173], off offset:64
	s_waitcnt vmcnt(0)
	ds_write_b128 v191, v[250:253]
	ds_write_b128 v191, v[162:165] offset:8192
	s_waitcnt lgkmcnt(0)
	global_load_dwordx4 v[250:253], v[176:177], off
	global_load_dwordx4 v[162:165], v[176:177], off offset:64
	s_waitcnt vmcnt(0)
	ds_write_b128 v191, v[250:253] offset:16384
	ds_write_b128 v191, v[162:165] offset:24576
	s_waitcnt lgkmcnt(0)
	global_load_dwordx4 v[162:165], v[168:169], off
	global_load_dwordx4 v[250:253], v[174:175], off
	s_waitcnt vmcnt(0)
	ds_write_b128 v220, v[162:165]
	s_waitcnt lgkmcnt(0)
.LBB0_365:
	v_lshl_add_u64 v[136:137], v[178:179], 0, s[88:89]
	v_add_co_u32_e32 v138, vcc, 0xe000000, v136
	s_waitcnt vmcnt(2)
	v_mul_f32_e32 v0, v171, v135
	v_addc_co_u32_e32 v139, vcc, 0, v137, vcc
	global_load_dwordx4 v[138:141], v[138:139], off
	v_add_co_u32_e32 v136, vcc, 0xe002000, v136
	v_cvt_pk_bf16_f32 v150, v134, v135
	v_lshl_add_u64 v[184:185], v[180:181], 0, s[88:89]
	s_nop 0
	v_addc_co_u32_e32 v137, vcc, 0, v137, vcc
	global_load_dwordx4 v[142:145], v[136:137], off offset:2048
	v_pk_fma_f32 v[136:137], v[170:171], v[134:135], v[0:1] op_sel_hi:[1,1,0] neg_lo:[0,0,1] neg_hi:[0,0,1]
	v_mul_f32_e32 v0, v167, v135
	v_pk_fma_f32 v[134:135], v[166:167], v[134:135], v[0:1] op_sel_hi:[1,1,0]
	v_add_co_u32_e32 v186, vcc, s20, v184
	s_add_i32 s4, s4, -1
	s_nop 0
	v_addc_co_u32_e32 v187, vcc, 0, v185, vcc
	v_add_co_u32_e32 v192, vcc, s95, v184
	v_lshl_add_u64 v[178:179], v[178:179], 0, s[82:83]
	s_nop 0
	v_addc_co_u32_e32 v193, vcc, 0, v185, vcc
	v_lshl_add_u64 v[180:181], v[180:181], 0, s[82:83]
	s_cmp_lg_u32 s4, 0
	global_load_dwordx2 v[218:219], v[186:187], off
	global_load_dwordx2 v[224:225], v[192:193], off offset:1024
	v_add_co_u32_e32 v194, vcc, s0, v184
	s_nop 1
	v_addc_co_u32_e32 v195, vcc, 0, v185, vcc
	global_load_dwordx2 v[254:255], v[194:195], off offset:2048
	v_add_co_u32_e32 v194, vcc, s96, v184
	s_nop 1
	v_addc_co_u32_e32 v195, vcc, 0, v185, vcc
	global_load_dword v223, v[194:195], off offset:3072
	global_load_dword v226, v[194:195], off offset:3076
	s_waitcnt vmcnt(6)
	v_mfma_f32_16x16x32_bf16 v[146:149], v[2:5], v[138:141], 0
	s_waitcnt vmcnt(5)
	v_mfma_f32_16x16x32_bf16 v[146:149], v[6:9], v[142:145], v[146:149]
	s_nop 7
	ds_write_b128 v238, v[146:149]
	v_mfma_f32_16x16x32_bf16 v[146:149], v[10:13], v[138:141], 0
	v_mfma_f32_16x16x32_bf16 v[146:149], v[14:17], v[142:145], v[146:149]
	s_nop 7
	ds_write_b128 v238, v[146:149] offset:64
	v_mfma_f32_16x16x32_bf16 v[146:149], v[18:21], v[138:141], 0
	v_mfma_f32_16x16x32_bf16 v[146:149], v[22:25], v[142:145], v[146:149]
	s_nop 7
	ds_write_b128 v238, v[146:149] offset:128
	v_mfma_f32_16x16x32_bf16 v[146:149], v[26:29], v[138:141], 0
	v_mfma_f32_16x16x32_bf16 v[146:149], v[30:33], v[142:145], v[146:149]
	s_nop 7
	ds_write_b128 v238, v[146:149] offset:192
	v_mfma_f32_16x16x32_bf16 v[146:149], v[34:37], v[138:141], 0
	v_mfma_f32_16x16x32_bf16 v[146:149], v[38:41], v[142:145], v[146:149]
	s_nop 7
	ds_write_b128 v238, v[146:149] offset:256
	v_mfma_f32_16x16x32_bf16 v[146:149], v[42:45], v[138:141], 0
	v_mfma_f32_16x16x32_bf16 v[146:149], v[46:49], v[142:145], v[146:149]
	s_nop 7
	ds_write_b128 v238, v[146:149] offset:320
	v_mfma_f32_16x16x32_bf16 v[146:149], v[50:53], v[138:141], 0
	v_mfma_f32_16x16x32_bf16 v[146:149], v[54:57], v[142:145], v[146:149]
	s_nop 7
	ds_write_b128 v238, v[146:149] offset:384
	v_mfma_f32_16x16x32_bf16 v[146:149], v[58:61], v[138:141], 0
	v_mfma_f32_16x16x32_bf16 v[146:149], v[62:65], v[142:145], v[146:149]
	s_nop 7
	ds_write_b128 v238, v[146:149] offset:448
	s_waitcnt lgkmcnt(0)
	ds_read2st64_b64 v[146:149], v241 offset1:1
	s_waitcnt lgkmcnt(0)
	v_pk_add_f32 v[134:135], v[134:135], v[146:147] op_sel:[0,1] op_sel_hi:[1,0]
	v_pk_add_f32 v[136:137], v[136:137], v[146:147]
	s_nop 0
	v_cvt_pk_bf16_f32 v0, v136, v134
	v_pk_mul_f32 v[134:135], v[166:167], v[134:135] op_sel_hi:[1,0]
	ds_write2st64_b32 v239, v150, v0 offset0:32 offset1:33
	v_pk_fma_f32 v[146:147], v[170:171], v[136:137], v[134:135] neg_lo:[0,0,1] neg_hi:[0,0,1]
	v_pk_fma_f32 v[134:135], v[170:171], v[136:137], v[134:135] op_sel_hi:[1,0,1]
	s_nop 0
	v_mov_b32_e32 v147, v135
	ds_read2st64_b64 v[134:137], v241 offset0:2 offset1:3
	v_pk_add_f32 v[146:147], v[146:147], v[148:149]
	s_nop 0
	v_mul_f32_e32 v0, v171, v147
	v_pk_fma_f32 v[148:149], v[170:171], v[146:147], v[0:1] op_sel_hi:[1,1,0] neg_lo:[0,0,1] neg_hi:[0,0,1]
	v_mul_f32_e32 v0, v171, v146
	v_cvt_pk_bf16_f32 v150, v146, v147
	v_pk_fma_f32 v[146:147], v[170:171], v[146:147], v[0:1] op_sel:[0,1,0] op_sel_hi:[1,0,0]
	s_waitcnt lgkmcnt(0)
	v_pk_add_f32 v[148:149], v[148:149], v[134:135]
	v_pk_add_f32 v[134:135], v[146:147], v[134:135] op_sel:[0,1] op_sel_hi:[1,0]
	s_nop 0
	v_cvt_pk_bf16_f32 v0, v148, v134
	v_pk_mul_f32 v[134:135], v[166:167], v[134:135] op_sel_hi:[1,0]
	ds_write2st64_b32 v239, v150, v0 offset0:34 offset1:35
	v_pk_fma_f32 v[146:147], v[170:171], v[148:149], v[134:135] neg_lo:[0,0,1] neg_hi:[0,0,1]
	v_pk_fma_f32 v[134:135], v[170:171], v[148:149], v[134:135] op_sel_hi:[1,0,1]
	s_nop 0
	v_mov_b32_e32 v147, v135
	v_pk_add_f32 v[146:147], v[146:147], v[136:137]
	ds_read2st64_b64 v[134:137], v241 offset0:4 offset1:5
	v_mul_f32_e32 v0, v171, v147
	v_pk_fma_f32 v[148:149], v[170:171], v[146:147], v[0:1] op_sel_hi:[1,1,0] neg_lo:[0,0,1] neg_hi:[0,0,1]
	v_mul_f32_e32 v0, v171, v146
	v_cvt_pk_bf16_f32 v150, v146, v147
	v_pk_fma_f32 v[146:147], v[170:171], v[146:147], v[0:1] op_sel:[0,1,0] op_sel_hi:[1,0,0]
	s_waitcnt lgkmcnt(0)
; #define LAS __attribute__((address_space(3)))
; __device__ __forceinline__ unsigned pk2(float lo, float hi) { unsigned r; asm("v_cvt_pk_bf16_f32 %0, %1, %2" : "=v"(r) : "v"(lo), "v"(hi)); return r; }
; __device__ __forceinline__ void lds_fence() { asm volatile("s_waitcnt lgkmcnt(0)" ::: "memory"); }
; __device__ __forceinline__ f32x4 mfma16(bf16x8 a, bf16x8 b, f32x4 c) { return __builtin_amdgcn_mfma_f32_16x16x32_bf16(a, b, c, 0, 0, 0); }
; template <int PASS>
; __device__ __forceinline__ void s5_pass(CArgs& a, LAS unsigned char* lds, int l, int panel) {
;     ...
;             for (int j = 0; j < 16; ++j) {
;                 if (PASS == 2) *(LAS unsigned*)(xh + j * 128 + 2 * lane) = pk2(Hr, Hi);
;                 const f32x2 lc = *(LAS f32x2*)(hl + j * 128 + 2 * lane);
;                 const float nr = a4r * Hr - a4i * Hi + lc.x, ni = a4r * Hi + a4i * Hr + lc.y;
;                 Hr = nr; Hi = ni;
;             }
;             lds_fence();
;             if (PASS == 2) {
;                 bf16x8 xhf[4];
; #pragma unroll
;                 for (int k4 = 0; k4 < 4; ++k4) xhf[k4] = *(const LAS bf16x8*)(xh + fr * 128 + 32 * k4 + 8 * fq);
; #pragma unroll
;                 for (int mt = 0; mt < 4; ++mt) {
;                     f32x4 acc = (f32x4){0.f, 0.f, 0.f, 0.f};
; #pragma unroll
;                     for (int ks = 0; ks < 2; ++ks) if (2 * ks <= mt) acc = mfma16(*(const bf16x8*)(Mg + (size_t)(16 * mt + fr) * 192 + 32 * ks + 8 * fq), xf[ks], acc);
; #pragma unroll
;                     for (int k4 = 0; k4 < 4; ++k4) acc = mfma16(mf[mt][k4], xhf[k4], acc);
	v_pk_add_f32 v[148:149], v[148:149], v[134:135]
	v_pk_add_f32 v[134:135], v[146:147], v[134:135] op_sel:[0,1] op_sel_hi:[1,0]
	s_nop 0
	v_cvt_pk_bf16_f32 v0, v148, v134
	v_pk_mul_f32 v[134:135], v[166:167], v[134:135] op_sel_hi:[1,0]
	ds_write2st64_b32 v239, v150, v0 offset0:36 offset1:37
	v_pk_fma_f32 v[146:147], v[170:171], v[148:149], v[134:135] neg_lo:[0,0,1] neg_hi:[0,0,1]
	v_pk_fma_f32 v[134:135], v[170:171], v[148:149], v[134:135] op_sel_hi:[1,0,1]
	s_nop 0
	v_mov_b32_e32 v147, v135
	v_pk_add_f32 v[146:147], v[146:147], v[136:137]
	ds_read2st64_b64 v[134:137], v241 offset0:6 offset1:7
	v_mul_f32_e32 v0, v171, v147
	v_pk_fma_f32 v[148:149], v[170:171], v[146:147], v[0:1] op_sel_hi:[1,1,0] neg_lo:[0,0,1] neg_hi:[0,0,1]
	v_mul_f32_e32 v0, v171, v146
	v_cvt_pk_bf16_f32 v150, v146, v147
	v_pk_fma_f32 v[146:147], v[170:171], v[146:147], v[0:1] op_sel:[0,1,0] op_sel_hi:[1,0,0]
	s_waitcnt lgkmcnt(0)
	v_pk_add_f32 v[148:149], v[148:149], v[134:135]
	v_pk_add_f32 v[134:135], v[146:147], v[134:135] op_sel:[0,1] op_sel_hi:[1,0]
	s_nop 0
	v_cvt_pk_bf16_f32 v0, v148, v134
	v_pk_mul_f32 v[134:135], v[166:167], v[134:135] op_sel_hi:[1,0]
	ds_write2st64_b32 v239, v150, v0 offset0:38 offset1:39
	v_pk_fma_f32 v[146:147], v[170:171], v[148:149], v[134:135] neg_lo:[0,0,1] neg_hi:[0,0,1]
	v_pk_fma_f32 v[134:135], v[170:171], v[148:149], v[134:135] op_sel_hi:[1,0,1]
	s_nop 0
	v_mov_b32_e32 v147, v135
	v_pk_add_f32 v[146:147], v[146:147], v[136:137]
	ds_read2st64_b64 v[134:137], v241 offset0:8 offset1:9
	v_mul_f32_e32 v0, v171, v147
	v_pk_fma_f32 v[148:149], v[170:171], v[146:147], v[0:1] op_sel_hi:[1,1,0] neg_lo:[0,0,1] neg_hi:[0,0,1]
	v_mul_f32_e32 v0, v171, v146
	v_cvt_pk_bf16_f32 v150, v146, v147
	v_pk_fma_f32 v[146:147], v[170:171], v[146:147], v[0:1] op_sel:[0,1,0] op_sel_hi:[1,0,0]
	s_waitcnt lgkmcnt(0)
	v_pk_add_f32 v[148:149], v[148:149], v[134:135]
	v_pk_add_f32 v[134:135], v[146:147], v[134:135] op_sel:[0,1] op_sel_hi:[1,0]
	s_nop 0
	v_cvt_pk_bf16_f32 v0, v148, v134
	v_pk_mul_f32 v[134:135], v[166:167], v[134:135] op_sel_hi:[1,0]
	ds_write2st64_b32 v239, v150, v0 offset0:40 offset1:41
	v_pk_fma_f32 v[146:147], v[170:171], v[148:149], v[134:135] neg_lo:[0,0,1] neg_hi:[0,0,1]
	v_pk_fma_f32 v[134:135], v[170:171], v[148:149], v[134:135] op_sel_hi:[1,0,1]
	s_nop 0
	v_mov_b32_e32 v147, v135
	v_pk_add_f32 v[146:147], v[146:147], v[136:137]
	ds_read2st64_b64 v[134:137], v241 offset0:10 offset1:11
	v_mul_f32_e32 v0, v171, v147
	v_pk_fma_f32 v[148:149], v[170:171], v[146:147], v[0:1] op_sel_hi:[1,1,0] neg_lo:[0,0,1] neg_hi:[0,0,1]
	v_mul_f32_e32 v0, v171, v146
	v_cvt_pk_bf16_f32 v150, v146, v147
	v_pk_fma_f32 v[146:147], v[170:171], v[146:147], v[0:1] op_sel:[0,1,0] op_sel_hi:[1,0,0]
	s_waitcnt lgkmcnt(0)
	v_pk_add_f32 v[148:149], v[148:149], v[134:135]
	v_pk_add_f32 v[134:135], v[146:147], v[134:135] op_sel:[0,1] op_sel_hi:[1,0]
	s_nop 0
	v_cvt_pk_bf16_f32 v0, v148, v134
	v_pk_mul_f32 v[134:135], v[170:171], v[134:135] op_sel_hi:[1,0]
	ds_write2st64_b32 v239, v150, v0 offset0:42 offset1:43
	v_pk_fma_f32 v[146:147], v[166:167], v[148:149], v[134:135]
	v_pk_fma_f32 v[134:135], v[166:167], v[148:149], v[134:135] op_sel_hi:[1,0,1] neg_lo:[0,0,1] neg_hi:[0,0,1]
	s_nop 0
	v_mov_b32_e32 v147, v135
	v_pk_add_f32 v[146:147], v[146:147], v[136:137] op_sel:[0,1] op_sel_hi:[1,0]
	ds_read2st64_b64 v[134:137], v241 offset0:12 offset1:13
	v_mul_f32_e32 v0, v171, v146
	v_pk_fma_f32 v[148:149], v[170:171], v[146:147], v[0:1] op_sel:[0,1,0] op_sel_hi:[1,0,0] neg_lo:[0,0,1] neg_hi:[0,0,1]
	v_mul_f32_e32 v0, v171, v147
	v_cvt_pk_bf16_f32 v150, v147, v146
	v_pk_fma_f32 v[146:147], v[170:171], v[146:147], v[0:1] op_sel_hi:[1,1,0]
	s_waitcnt lgkmcnt(0)
	v_pk_add_f32 v[148:149], v[148:149], v[134:135]
	v_pk_add_f32 v[134:135], v[146:147], v[134:135] op_sel:[0,1] op_sel_hi:[1,0]
	s_nop 0
	v_cvt_pk_bf16_f32 v0, v148, v134
	v_pk_mul_f32 v[134:135], v[170:171], v[134:135] op_sel_hi:[1,0]
	ds_write2st64_b32 v239, v150, v0 offset0:44 offset1:45
	v_pk_fma_f32 v[146:147], v[166:167], v[148:149], v[134:135]
	v_pk_fma_f32 v[134:135], v[166:167], v[148:149], v[134:135] op_sel_hi:[1,0,1] neg_lo:[0,0,1] neg_hi:[0,0,1]
	s_nop 0
	v_mov_b32_e32 v147, v135
	v_pk_add_f32 v[146:147], v[146:147], v[136:137] op_sel:[0,1] op_sel_hi:[1,0]
	ds_read2st64_b64 v[134:137], v241 offset0:14 offset1:15
	v_mul_f32_e32 v0, v171, v146
	v_pk_fma_f32 v[148:149], v[170:171], v[146:147], v[0:1] op_sel:[0,1,0] op_sel_hi:[1,0,0] neg_lo:[0,0,1] neg_hi:[0,0,1]
	v_mul_f32_e32 v0, v171, v147
	v_cvt_pk_bf16_f32 v150, v147, v146
	v_pk_fma_f32 v[146:147], v[170:171], v[146:147], v[0:1] op_sel_hi:[1,1,0]
	s_waitcnt lgkmcnt(0)
	v_pk_add_f32 v[162:163], v[148:149], v[134:135]
	v_pk_add_f32 v[134:135], v[146:147], v[134:135] op_sel:[0,1] op_sel_hi:[1,0]
	s_nop 0
	v_cvt_pk_bf16_f32 v0, v162, v134
	ds_write2st64_b32 v239, v150, v0 offset0:46 offset1:47
	v_pk_mul_f32 v[164:165], v[166:167], v[134:135] op_sel_hi:[1,0]
	s_waitcnt lgkmcnt(0)
	ds_read_b128 v[146:149], v240 offset:8192
	ds_read_b128 v[150:153], v240 offset:8256
	ds_read_b128 v[154:157], v240 offset:8320
	ds_read_b128 v[158:161], v240 offset:8384
	v_pk_fma_f32 v[134:135], v[170:171], v[162:163], v[164:165] neg_lo:[0,0,1] neg_hi:[0,0,1]
	v_pk_fma_f32 v[162:163], v[170:171], v[162:163], v[164:165] op_sel_hi:[1,0,1]
	v_mov_b32_e32 v135, v163
	ds_read_b128 v[162:165], v220
	s_waitcnt vmcnt(0) lgkmcnt(0)
	v_mfma_f32_16x16x32_bf16 v[162:165], v[162:165], v[138:141], 0
	v_lshlrev_b32_e32 v0, 16, v218
	v_pk_add_f32 v[134:135], v[134:135], v[136:137]
	s_waitcnt lgkmcnt(3)
	v_mfma_f32_16x16x32_bf16 v[162:165], v[66:69], v[146:149], v[162:165]
	s_waitcnt lgkmcnt(2)
; __device__ __forceinline__ unsigned pk2(float lo, float hi) { unsigned r; asm("v_cvt_pk_bf16_f32 %0, %1, %2" : "=v"(r) : "v"(lo), "v"(hi)); return r; }
; __device__ __forceinline__ float bflo(unsigned w) { return __uint_as_float(w << 16); }
; __device__ __forceinline__ float bfhi(unsigned w) { return __uint_as_float(w & 0xffff0000u); }
; __device__ __forceinline__ float gelu_tanh(float x) { const float u = 0.7978845608028654f * (x + 0.044715f * x * x * x); return x * __builtin_amdgcn_rcpf(1.f + fexp(-2.f * u)); }
; __device__ __forceinline__ f32x4 mfma16(bf16x8 a, bf16x8 b, f32x4 c) { return __builtin_amdgcn_mfma_f32_16x16x32_bf16(a, b, c, 0, 0, 0); }
; template <int PASS>
; __device__ __forceinline__ void s5_pass(CArgs& a, LAS unsigned char* lds, int l, int panel) {
;     ...
;                 for (int mt = 0; mt < 4; ++mt) {
;                     f32x4 acc = (f32x4){0.f, 0.f, 0.f, 0.f};
; #pragma unroll
;                     for (int ks = 0; ks < 2; ++ks) if (2 * ks <= mt) acc = mfma16(*(const bf16x8*)(Mg + (size_t)(16 * mt + fr) * 192 + 32 * ks + 8 * fq), xf[ks], acc);
; #pragma unroll
;                     for (int k4 = 0; k4 < 4; ++k4) acc = mfma16(mf[mt][k4], xhf[k4], acc);
;                     const int tok = (16 * nt + fr) * 4 + mt, ch = g * 16 + 4 * fq;
;                     const u32x2 uv = *(const u32x2*)(Zp + (size_t)tok * ZROWB + (C_S5U + ch) * 2);
;                     const float y0 = gelu_tanh(acc[0] + dsk[0] * bflo(uv.x)), y1 = gelu_tanh(acc[1] + dsk[1] * bfhi(uv.x));
;                     const float y2 = gelu_tanh(acc[2] + dsk[2] * bflo(uv.y)), y3 = gelu_tanh(acc[3] + dsk[3] * bfhi(uv.y));
;                     u32x2 w; w.x = pk2(y0, y1); w.y = pk2(y2, y3);
;                     *(u32x2*)(YS5 + (size_t)tok * 512 + ch * 2) = w;
	v_mfma_f32_16x16x32_bf16 v[162:165], v[70:73], v[150:153], v[162:165]
	s_waitcnt lgkmcnt(1)
	v_mfma_f32_16x16x32_bf16 v[162:165], v[74:77], v[154:157], v[162:165]
	s_waitcnt lgkmcnt(0)
	v_mfma_f32_16x16x32_bf16 v[162:165], v[78:81], v[158:161], v[162:165]
	s_nop 7
	v_fma_f32 v0, v122, v0, v162
	v_mul_f32_e32 v162, 0x3d372713, v0
	v_mul_f32_e32 v162, v0, v162
	v_fma_f32 v162, v0, v162, v0
	v_mul_f32_e32 v162, 0x3f4c422a, v162
	v_mul_f32_e32 v162, -2.0, v162
	v_mul_f32_e32 v162, 0x3fb8aa3b, v162
	v_exp_f32_e32 v162, v162
	s_nop 0
	v_add_f32_e32 v162, 1.0, v162
	v_rcp_f32_e32 v162, v162
	s_nop 0
	v_mul_f32_e32 v0, v0, v162
	v_and_b32_e32 v162, 0xffff0000, v218
	v_fma_f32 v162, v123, v162, v163
	v_mul_f32_e32 v163, 0x3d372713, v162
	v_mul_f32_e32 v163, v162, v163
	v_fma_f32 v163, v162, v163, v162
	v_mul_f32_e32 v163, 0x3f4c422a, v163
	v_mul_f32_e32 v163, -2.0, v163
	v_mul_f32_e32 v163, 0x3fb8aa3b, v163
	v_exp_f32_e32 v163, v163
	s_nop 0
	v_add_f32_e32 v163, 1.0, v163
	v_rcp_f32_e32 v163, v163
	s_nop 0
	v_mul_f32_e32 v162, v162, v163
	v_lshlrev_b32_e32 v163, 16, v219
	v_fma_f32 v163, v124, v163, v164
	v_mul_f32_e32 v164, 0x3d372713, v163
	v_mul_f32_e32 v164, v163, v164
	v_fma_f32 v164, v163, v164, v163
	v_mul_f32_e32 v164, 0x3f4c422a, v164
	v_mul_f32_e32 v164, -2.0, v164
	v_mul_f32_e32 v164, 0x3fb8aa3b, v164
	v_exp_f32_e32 v164, v164
	v_cvt_pk_bf16_f32 v162, v0, v162
	s_nop 0
	v_add_f32_e32 v164, 1.0, v164
	v_rcp_f32_e32 v164, v164
	s_nop 0
	v_mul_f32_e32 v163, v163, v164
	v_and_b32_e32 v164, 0xffff0000, v219
	v_fmac_f32_e32 v165, v125, v164
	v_mul_f32_e32 v164, 0x3d372713, v165
	v_mul_f32_e32 v164, v165, v164
	v_fma_f32 v164, v165, v164, v165
	v_mul_f32_e32 v164, 0x3f4c422a, v164
	v_mul_f32_e32 v164, -2.0, v164
	v_mul_f32_e32 v164, 0x3fb8aa3b, v164
	v_exp_f32_e32 v164, v164
	v_lshl_add_u64 v[186:187], v[182:183], 0, s[88:89]
	v_lshl_add_u64 v[182:183], v[182:183], 0, s[14:15]
	v_add_f32_e32 v164, 1.0, v164
	v_rcp_f32_e32 v164, v164
	s_nop 0
	v_mul_f32_e32 v164, v165, v164
	v_cvt_pk_bf16_f32 v163, v163, v164
	global_store_dwordx2 v[186:187], v[162:163], off offset:-1024
	v_mfma_f32_16x16x32_bf16 v[162:165], v[250:253], v[138:141], 0
	v_lshlrev_b32_e32 v0, 16, v224
	v_mfma_f32_16x16x32_bf16 v[162:165], v[82:85], v[146:149], v[162:165]
	v_mfma_f32_16x16x32_bf16 v[162:165], v[86:89], v[150:153], v[162:165]
	v_mfma_f32_16x16x32_bf16 v[162:165], v[90:93], v[154:157], v[162:165]
	v_mfma_f32_16x16x32_bf16 v[162:165], v[94:97], v[158:161], v[162:165]
	s_nop 7
	v_fma_f32 v0, v122, v0, v162
	v_mul_f32_e32 v162, 0x3d372713, v0
	v_mul_f32_e32 v162, v0, v162
	v_fma_f32 v162, v0, v162, v0
	v_mul_f32_e32 v162, 0x3f4c422a, v162
	v_mul_f32_e32 v162, -2.0, v162
	v_mul_f32_e32 v162, 0x3fb8aa3b, v162
	v_exp_f32_e32 v162, v162
	s_nop 0
	v_add_f32_e32 v162, 1.0, v162
	v_rcp_f32_e32 v162, v162
	s_nop 0
	v_mul_f32_e32 v0, v0, v162
	v_and_b32_e32 v162, 0xffff0000, v224
	v_fma_f32 v162, v123, v162, v163
	v_mul_f32_e32 v163, 0x3d372713, v162
	v_mul_f32_e32 v163, v162, v163
	v_fma_f32 v163, v162, v163, v162
	v_mul_f32_e32 v163, 0x3f4c422a, v163
	v_mul_f32_e32 v163, -2.0, v163
	v_mul_f32_e32 v163, 0x3fb8aa3b, v163
	v_exp_f32_e32 v163, v163
	s_nop 0
	v_add_f32_e32 v163, 1.0, v163
	v_rcp_f32_e32 v163, v163
	s_nop 0
	v_mul_f32_e32 v162, v162, v163
	v_lshlrev_b32_e32 v163, 16, v225
	v_fma_f32 v163, v124, v163, v164
	v_mul_f32_e32 v164, 0x3d372713, v163
	v_mul_f32_e32 v164, v163, v164
	v_fma_f32 v164, v163, v164, v163
	v_mul_f32_e32 v164, 0x3f4c422a, v164
	v_mul_f32_e32 v164, -2.0, v164
	v_mul_f32_e32 v164, 0x3fb8aa3b, v164
	v_exp_f32_e32 v164, v164
	v_cvt_pk_bf16_f32 v162, v0, v162
	s_nop 0
	v_add_f32_e32 v164, 1.0, v164
	v_rcp_f32_e32 v164, v164
	s_nop 0
	v_mul_f32_e32 v163, v163, v164
	v_and_b32_e32 v164, 0xffff0000, v225
	v_fmac_f32_e32 v165, v125, v164
	v_mul_f32_e32 v164, 0x3d372713, v165
	v_mul_f32_e32 v164, v165, v164
	v_fma_f32 v164, v165, v164, v165
	v_mul_f32_e32 v164, 0x3f4c422a, v164
	v_mul_f32_e32 v164, -2.0, v164
	v_mul_f32_e32 v164, 0x3fb8aa3b, v164
	v_exp_f32_e32 v164, v164
	s_nop 0
	v_add_f32_e32 v164, 1.0, v164
	v_rcp_f32_e32 v164, v164
	s_nop 0
	v_mul_f32_e32 v164, v165, v164
	v_cvt_pk_bf16_f32 v163, v163, v164
	global_store_dwordx2 v[186:187], v[162:163], off offset:-512
	ds_read_b128 v[162:165], v191
	s_nop 0
	ds_read_b128 v[192:195], v191 offset:8192
	s_waitcnt lgkmcnt(1)
	v_mfma_f32_16x16x32_bf16 v[162:165], v[162:165], v[138:141], 0
	s_waitcnt lgkmcnt(0)
; __device__ __forceinline__ unsigned pk2(float lo, float hi) { unsigned r; asm("v_cvt_pk_bf16_f32 %0, %1, %2" : "=v"(r) : "v"(lo), "v"(hi)); return r; }
; __device__ __forceinline__ float bflo(unsigned w) { return __uint_as_float(w << 16); }
; __device__ __forceinline__ float bfhi(unsigned w) { return __uint_as_float(w & 0xffff0000u); }
; __device__ __forceinline__ float gelu_tanh(float x) { const float u = 0.7978845608028654f * (x + 0.044715f * x * x * x); return x * __builtin_amdgcn_rcpf(1.f + fexp(-2.f * u)); }
; __device__ __forceinline__ f32x4 mfma16(bf16x8 a, bf16x8 b, f32x4 c) { return __builtin_amdgcn_mfma_f32_16x16x32_bf16(a, b, c, 0, 0, 0); }
; template <int PASS>
; __device__ __forceinline__ void s5_pass(CArgs& a, LAS unsigned char* lds, int l, int panel) {
;     ...
;                 for (int mt = 0; mt < 4; ++mt) {
;                     f32x4 acc = (f32x4){0.f, 0.f, 0.f, 0.f};
; #pragma unroll
;                     for (int ks = 0; ks < 2; ++ks) if (2 * ks <= mt) acc = mfma16(*(const bf16x8*)(Mg + (size_t)(16 * mt + fr) * 192 + 32 * ks + 8 * fq), xf[ks], acc);
; #pragma unroll
;                     for (int k4 = 0; k4 < 4; ++k4) acc = mfma16(mf[mt][k4], xhf[k4], acc);
;                     const int tok = (16 * nt + fr) * 4 + mt, ch = g * 16 + 4 * fq;
;                     const u32x2 uv = *(const u32x2*)(Zp + (size_t)tok * ZROWB + (C_S5U + ch) * 2);
;                     const float y0 = gelu_tanh(acc[0] + dsk[0] * bflo(uv.x)), y1 = gelu_tanh(acc[1] + dsk[1] * bfhi(uv.x));
;                     const float y2 = gelu_tanh(acc[2] + dsk[2] * bflo(uv.y)), y3 = gelu_tanh(acc[3] + dsk[3] * bfhi(uv.y));
;                     u32x2 w; w.x = pk2(y0, y1); w.y = pk2(y2, y3);
;                     *(u32x2*)(YS5 + (size_t)tok * 512 + ch * 2) = w;
;                 }
; template <int PASS>
; __device__ __forceinline__ void gla_pass(CArgs& a, LAS unsigned char* lds, int l, int panel) {
;     ...
;     GLA_LOAD(0);
	v_mfma_f32_16x16x32_bf16 v[162:165], v[192:195], v[142:145], v[162:165]
	v_mfma_f32_16x16x32_bf16 v[162:165], v[98:101], v[146:149], v[162:165]
	v_lshlrev_b32_e32 v0, 16, v254
	v_mfma_f32_16x16x32_bf16 v[162:165], v[102:105], v[150:153], v[162:165]
	v_mfma_f32_16x16x32_bf16 v[162:165], v[106:109], v[154:157], v[162:165]
	v_mfma_f32_16x16x32_bf16 v[162:165], v[110:113], v[158:161], v[162:165]
	s_nop 7
	v_fma_f32 v0, v122, v0, v162
	v_mul_f32_e32 v162, 0x3d372713, v0
	v_mul_f32_e32 v162, v0, v162
	v_fma_f32 v162, v0, v162, v0
	v_mul_f32_e32 v162, 0x3f4c422a, v162
	v_mul_f32_e32 v162, -2.0, v162
	v_mul_f32_e32 v162, 0x3fb8aa3b, v162
	v_exp_f32_e32 v162, v162
	s_nop 0
	v_add_f32_e32 v162, 1.0, v162
	v_rcp_f32_e32 v162, v162
	s_nop 0
	v_mul_f32_e32 v0, v0, v162
	v_and_b32_e32 v162, 0xffff0000, v254
	v_fma_f32 v162, v123, v162, v163
	v_mul_f32_e32 v163, 0x3d372713, v162
	v_mul_f32_e32 v163, v162, v163
	v_fma_f32 v163, v162, v163, v162
	v_mul_f32_e32 v163, 0x3f4c422a, v163
	v_mul_f32_e32 v163, -2.0, v163
	v_mul_f32_e32 v163, 0x3fb8aa3b, v163
	v_exp_f32_e32 v163, v163
	s_nop 0
	v_add_f32_e32 v163, 1.0, v163
	v_rcp_f32_e32 v163, v163
	s_nop 0
	v_mul_f32_e32 v162, v162, v163
	v_lshlrev_b32_e32 v163, 16, v255
	v_fma_f32 v163, v124, v163, v164
	v_mul_f32_e32 v164, 0x3d372713, v163
	v_mul_f32_e32 v164, v163, v164
	v_fma_f32 v164, v163, v164, v163
	v_mul_f32_e32 v164, 0x3f4c422a, v164
	v_mul_f32_e32 v164, -2.0, v164
	v_mul_f32_e32 v164, 0x3fb8aa3b, v164
	v_exp_f32_e32 v164, v164
	v_cvt_pk_bf16_f32 v162, v0, v162
	s_nop 0
	v_add_f32_e32 v164, 1.0, v164
	v_rcp_f32_e32 v164, v164
	s_nop 0
	v_mul_f32_e32 v163, v163, v164
	v_and_b32_e32 v164, 0xffff0000, v255
	v_fmac_f32_e32 v165, v125, v164
	v_mul_f32_e32 v164, 0x3d372713, v165
	v_mul_f32_e32 v164, v165, v164
	v_fma_f32 v164, v165, v164, v165
	v_mul_f32_e32 v164, 0x3f4c422a, v164
	v_mul_f32_e32 v164, -2.0, v164
	v_mul_f32_e32 v164, 0x3fb8aa3b, v164
	v_exp_f32_e32 v164, v164
	s_nop 0
	v_add_f32_e32 v164, 1.0, v164
	v_rcp_f32_e32 v164, v164
	s_nop 0
	v_mul_f32_e32 v164, v165, v164
	v_cvt_pk_bf16_f32 v163, v163, v164
	global_store_dwordx2 v[186:187], v[162:163], off
	ds_read_b128 v[162:165], v191 offset:16384
	s_waitcnt lgkmcnt(0)
	v_mfma_f32_16x16x32_bf16 v[138:141], v[162:165], v[138:141], 0
	ds_read_b128 v[162:165], v191 offset:24576
	s_waitcnt lgkmcnt(0)
	v_mfma_f32_16x16x32_bf16 v[138:141], v[162:165], v[142:145], v[138:141]
	v_mfma_f32_16x16x32_bf16 v[138:141], v[114:117], v[146:149], v[138:141]
	v_lshlrev_b32_e32 v0, 16, v223
	v_mfma_f32_16x16x32_bf16 v[138:141], v[118:121], v[150:153], v[138:141]
	v_mfma_f32_16x16x32_bf16 v[138:141], v[126:129], v[154:157], v[138:141]
	v_mfma_f32_16x16x32_bf16 v[138:141], v[130:133], v[158:161], v[138:141]
	s_nop 7
	v_fma_f32 v0, v122, v0, v138
	v_mul_f32_e32 v138, 0x3d372713, v0
	v_mul_f32_e32 v138, v0, v138
	v_fma_f32 v138, v0, v138, v0
	v_mul_f32_e32 v138, 0x3f4c422a, v138
	v_mul_f32_e32 v138, -2.0, v138
	v_mul_f32_e32 v138, 0x3fb8aa3b, v138
	v_exp_f32_e32 v138, v138
	s_nop 0
	v_add_f32_e32 v138, 1.0, v138
	v_rcp_f32_e32 v138, v138
	s_nop 0
	v_mul_f32_e32 v0, v0, v138
	v_and_b32_e32 v138, 0xffff0000, v223
	v_fma_f32 v138, v123, v138, v139
	v_mul_f32_e32 v139, 0x3d372713, v138
	v_mul_f32_e32 v139, v138, v139
	v_fma_f32 v139, v138, v139, v138
	v_mul_f32_e32 v139, 0x3f4c422a, v139
	v_mul_f32_e32 v139, -2.0, v139
	v_mul_f32_e32 v139, 0x3fb8aa3b, v139
	v_exp_f32_e32 v139, v139
	s_nop 0
	v_add_f32_e32 v139, 1.0, v139
	v_rcp_f32_e32 v139, v139
	s_nop 0
	v_mul_f32_e32 v138, v138, v139
	v_lshlrev_b32_e32 v139, 16, v226
	v_fma_f32 v139, v124, v139, v140
	v_mul_f32_e32 v140, 0x3d372713, v139
	v_mul_f32_e32 v140, v139, v140
	v_fma_f32 v140, v139, v140, v139
	v_mul_f32_e32 v140, 0x3f4c422a, v140
	v_mul_f32_e32 v140, -2.0, v140
	v_mul_f32_e32 v140, 0x3fb8aa3b, v140
	v_exp_f32_e32 v140, v140
	v_cvt_pk_bf16_f32 v138, v0, v138
	s_nop 0
	v_add_f32_e32 v140, 1.0, v140
	v_rcp_f32_e32 v140, v140
	s_nop 0
	v_mul_f32_e32 v139, v139, v140
	v_and_b32_e32 v140, 0xffff0000, v226
	v_fmac_f32_e32 v141, v125, v140
	v_mul_f32_e32 v140, 0x3d372713, v141
	v_mul_f32_e32 v140, v141, v140
	v_fma_f32 v140, v141, v140, v141
	v_mul_f32_e32 v140, 0x3f4c422a, v140
	v_mul_f32_e32 v140, -2.0, v140
	v_mul_f32_e32 v140, 0x3fb8aa3b, v140
	v_exp_f32_e32 v140, v140
	s_nop 0
	v_add_f32_e32 v140, 1.0, v140
	v_rcp_f32_e32 v140, v140
	s_nop 0
	v_mul_f32_e32 v140, v141, v140
	v_cvt_pk_bf16_f32 v139, v139, v140
	global_store_dwordx2 v[186:187], v[138:139], off offset:512
	s_waitcnt lgkmcnt(0)
	s_cbranch_scc1 .LBB0_365
	v_readlane_b32 s38, v249, 0
	v_readlane_b32 s39, v249, 1
	v_mov_b32_e32 v10, v189
	s_barrier
	s_load_dwordx2 s[42:43], s[38:39], 0xf8
	v_ashrrev_i32_e32 v11, 8, v10
	v_mov_b32_e32 v20, v1
	v_mov_b32_e32 v21, v1
	v_and_b32_e32 v87, 63, v10
	s_waitcnt lgkmcnt(0)
	s_add_u32 s1, s42, s88
	s_addc_u32 s2, s43, s89
	s_add_u32 s26, s1, 0xe000000
	v_and_b32_e32 v86, 15, v10
	s_addc_u32 s27, s2, 0
	v_lshlrev_b32_e32 v144, 5, v11
	v_and_b32_e32 v88, 48, v10
	v_mov_b32_e32 v89, v1
	v_mov_b32_e32 v18, v1
	v_mov_b32_e32 v19, v1
	v_mov_b64_e32 v[24:25], v[20:21]
	v_cmp_gt_u32_e64 s[2:3], 32, v87
	v_or_b32_e32 v3, v144, v86
	v_lshl_add_u64 v[90:91], s[26:27], 0, v[88:89]
	v_mov_b64_e32 v[22:23], v[18:19]
	s_and_saveexec_b64 s[8:9], s[2:3]
	v_readlane_b32 s10, v248, 36
	v_readlane_b32 s11, v248, 37
	s_cbranch_execz .LBB0_368
	v_mad_i64_i32 v[4:5], s[4:5], v3, s90, v[90:91]
	v_add_co_u32_e32 v4, vcc, 0x1000, v4
	s_nop 1
	v_addc_co_u32_e32 v5, vcc, 0, v5, vcc
	global_load_dwordx4 v[22:25], v[4:5], off offset:512

; __global__ void __launch_bounds__(512, 2) fwd_megakernel(Args a) {
	.amdhsa_kernel _Z14fwd_megakernel4Args
		.amdhsa_group_segment_fixed_size 0
		.amdhsa_private_segment_fixed_size 0
		.amdhsa_kernarg_size 512
		.amdhsa_user_sgpr_count 2
		.amdhsa_user_sgpr_dispatch_ptr 0
		.amdhsa_user_sgpr_queue_ptr 0
		.amdhsa_user_sgpr_kernarg_segment_ptr 1
		.amdhsa_user_sgpr_dispatch_id 0
		.amdhsa_user_sgpr_kernarg_preload_length 0
		.amdhsa_user_sgpr_kernarg_preload_offset 0
		.amdhsa_user_sgpr_private_segment_size 0
		.amdhsa_uses_dynamic_stack 0
		.amdhsa_enable_private_segment 0
		.amdhsa_system_sgpr_workgroup_id_x 1
		.amdhsa_system_sgpr_workgroup_id_y 0
		.amdhsa_system_sgpr_workgroup_id_z 0
		.amdhsa_system_sgpr_workgroup_info 0
		.amdhsa_system_vgpr_workitem_id 2
		.amdhsa_next_free_vgpr 256
		.amdhsa_next_free_sgpr 102
		.amdhsa_accum_offset 256
		.amdhsa_reserve_vcc 1
		.amdhsa_float_round_mode_32 0
		.amdhsa_float_round_mode_16_64 0
		.amdhsa_float_denorm_mode_32 3
		.amdhsa_float_denorm_mode_16_64 3
		.amdhsa_dx10_clamp 1
		.amdhsa_ieee_mode 1
		.amdhsa_fp16_overflow 0
		.amdhsa_tg_split 0
		.amdhsa_exception_fp_ieee_invalid_op 0
		.amdhsa_exception_fp_denorm_src 0
		.amdhsa_exception_fp_ieee_div_zero 0
		.amdhsa_exception_fp_ieee_overflow 0
		.amdhsa_exception_fp_ieee_underflow 0
		.amdhsa_exception_fp_ieee_inexact 0
		.amdhsa_exception_int_div_zero 0
	.end_amdhsa_kernel

; __global__ void __launch_bounds__(512, 2) fwd_megakernel(Args a) {
amdhsa.kernels:
  - .agpr_count:     0
    .args:
      - .offset:         0
        .size:           256
        .value_kind:     by_value
      - .offset:         256
        .size:           4
        .value_kind:     hidden_block_count_x
      - .offset:         260
        .size:           4
        .value_kind:     hidden_block_count_y
      - .offset:         264
        .size:           4
        .value_kind:     hidden_block_count_z
      - .offset:         268
        .size:           2
        .value_kind:     hidden_group_size_x
      - .offset:         270
        .size:           2
        .value_kind:     hidden_group_size_y
      - .offset:         272
        .size:           2
        .value_kind:     hidden_group_size_z
      - .offset:         274
        .size:           2
        .value_kind:     hidden_remainder_x
      - .offset:         276
        .size:           2
        .value_kind:     hidden_remainder_y
      - .offset:         278
        .size:           2
        .value_kind:     hidden_remainder_z
      - .offset:         296
        .size:           8
        .value_kind:     hidden_global_offset_x
      - .offset:         304
        .size:           8
        .value_kind:     hidden_global_offset_y
      - .offset:         312
        .size:           8
        .value_kind:     hidden_global_offset_z
      - .offset:         320
        .size:           2
        .value_kind:     hidden_grid_dims
      - .offset:         344
        .size:           8
        .value_kind:     hidden_multigrid_sync_arg
      - .offset:         376
        .size:           4
        .value_kind:     hidden_dynamic_lds_size
    .group_segment_fixed_size: 0
    .kernarg_segment_align: 8
    .kernarg_segment_size: 512
    .language:       OpenCL C
    .language_version:
      - 2
      - 0
    .max_flat_workgroup_size: 512
    .name:           _Z14fwd_megakernel4Args
    .private_segment_fixed_size: 0
    .sgpr_count:     108
    .sgpr_spill_count: 104
    .symbol:         _Z14fwd_megakernel4Args.kd
    .uniform_work_group_size: 1
    .uses_dynamic_stack: false
    .vgpr_count:     256
    .vgpr_spill_count: 0
    .wavefront_size: 64
